# v23 plus the redundant back-to-back s_setprio 0 / s_setprio 1 pairs in the middle of each 32-MFMA block of the five GEMM K-loops removed
# baseline (speedup 1.0000x reference)
.LBB0_131:
	ds_read_b128 v[152:155], v145
	ds_read_b128 v[156:159], v145 offset:1024
	ds_read_b128 v[160:163], v145 offset:2048
	ds_read_b128 v[168:171], v145 offset:3072
	ds_read_b128 v[172:175], v146
	ds_read_b128 v[176:179], v146 offset:1024
	ds_read_b128 v[180:183], v146 offset:2048
	ds_read_b128 v[184:187], v146 offset:3072
	s_add_i32 s26, s24, 0xfdfc0080
	s_cmp_lg_u32 s34, 12
	s_cselect_b32 s26, s26, 0
	s_add_u32 s36, s8, s26
	s_addc_u32 s37, s9, 0
	s_add_u32 s26, s6, s26
	s_addc_u32 s27, s7, 0
	s_mov_b32 m0, s35
	v_lshl_add_u64 v[220:221], v[140:141], 0, s[24:25]
	ds_read_b128 v[188:191], v147
	ds_read_b128 v[192:195], v147 offset:1024
	ds_read_b128 v[196:199], v147 offset:2048
	ds_read_b128 v[200:203], v147 offset:3072
	ds_read_b128 v[204:207], v147 offset:4096
	ds_read_b128 v[208:211], v147 offset:5120
	ds_read_b128 v[212:215], v147 offset:6144
	ds_read_b128 v[216:219], v147 offset:7168
	global_load_lds_dwordx4 v[220:221], off
	v_lshl_add_u64 v[220:221], v[142:143], 0, s[24:25]
	s_mov_b32 m0, s38
	s_nop 0
	global_load_lds_dwordx4 v[220:221], off
	s_waitcnt vmcnt(8)
	s_waitcnt lgkmcnt(0)
	s_barrier
	s_setprio 1
	s_waitcnt lgkmcnt(0)
	v_mfma_f32_16x16x32_bf16 v[124:127], v[152:155], v[188:191], v[124:127]
	v_mfma_f32_16x16x32_bf16 v[120:123], v[160:163], v[188:191], v[120:123]
	v_mfma_f32_16x16x32_bf16 v[108:111], v[152:155], v[196:199], v[108:111]
	v_mfma_f32_16x16x32_bf16 v[104:107], v[160:163], v[196:199], v[104:107]
	v_mfma_f32_16x16x32_bf16 v[92:95], v[152:155], v[204:207], v[92:95]
	v_mfma_f32_16x16x32_bf16 v[88:91], v[160:163], v[204:207], v[88:91]
	v_mfma_f32_16x16x32_bf16 v[76:79], v[152:155], v[212:215], v[76:79]
	v_mfma_f32_16x16x32_bf16 v[72:75], v[160:163], v[212:215], v[72:75]
	v_mfma_f32_16x16x32_bf16 v[124:127], v[156:159], v[192:195], v[124:127]
	v_mfma_f32_16x16x32_bf16 v[120:123], v[168:171], v[192:195], v[120:123]
	v_mfma_f32_16x16x32_bf16 v[108:111], v[156:159], v[200:203], v[108:111]
	v_mfma_f32_16x16x32_bf16 v[104:107], v[168:171], v[200:203], v[104:107]
	v_mfma_f32_16x16x32_bf16 v[92:95], v[156:159], v[208:211], v[92:95]
	v_mfma_f32_16x16x32_bf16 v[88:91], v[168:171], v[208:211], v[88:91]
	v_mfma_f32_16x16x32_bf16 v[76:79], v[156:159], v[216:219], v[76:79]
	v_mfma_f32_16x16x32_bf16 v[72:75], v[168:171], v[216:219], v[72:75]
	v_mfma_f32_16x16x32_bf16 v[116:119], v[172:175], v[188:191], v[116:119]
	v_mfma_f32_16x16x32_bf16 v[112:115], v[180:183], v[188:191], v[112:115]
	v_mfma_f32_16x16x32_bf16 v[100:103], v[172:175], v[196:199], v[100:103]
	v_mfma_f32_16x16x32_bf16 v[96:99], v[180:183], v[196:199], v[96:99]
	v_mfma_f32_16x16x32_bf16 v[84:87], v[172:175], v[204:207], v[84:87]
	v_mfma_f32_16x16x32_bf16 v[80:83], v[180:183], v[204:207], v[80:83]
	v_mfma_f32_16x16x32_bf16 v[68:71], v[172:175], v[212:215], v[68:71]
	v_mfma_f32_16x16x32_bf16 v[64:67], v[180:183], v[212:215], v[64:67]
	v_mfma_f32_16x16x32_bf16 v[116:119], v[176:179], v[192:195], v[116:119]
	v_mfma_f32_16x16x32_bf16 v[112:115], v[184:187], v[192:195], v[112:115]
	v_mfma_f32_16x16x32_bf16 v[100:103], v[176:179], v[200:203], v[100:103]
	v_mfma_f32_16x16x32_bf16 v[96:99], v[184:187], v[200:203], v[96:99]
	v_mfma_f32_16x16x32_bf16 v[84:87], v[176:179], v[208:211], v[84:87]
	v_mfma_f32_16x16x32_bf16 v[80:83], v[184:187], v[208:211], v[80:83]
	v_mfma_f32_16x16x32_bf16 v[68:71], v[176:179], v[216:219], v[68:71]
	v_mfma_f32_16x16x32_bf16 v[64:67], v[184:187], v[216:219], v[64:67]
	s_setprio 0
	s_barrier
	s_mov_b32 m0, s39
	v_lshl_add_u64 v[220:221], s[26:27], 0, v[130:131]
	s_add_u32 s48, s26, 0x40000
	ds_read_b128 v[188:191], v147 offset:16384
	ds_read_b128 v[192:195], v147 offset:17408
	ds_read_b128 v[196:199], v147 offset:18432
	ds_read_b128 v[200:203], v147 offset:19456
	ds_read_b128 v[204:207], v147 offset:20480
	ds_read_b128 v[208:211], v147 offset:21504
	ds_read_b128 v[212:215], v147 offset:22528
	ds_read_b128 v[216:219], v147 offset:23552
	global_load_lds_dwordx4 v[220:221], off
	v_lshl_add_u64 v[222:223], s[26:27], 0, v[134:135]
	s_mov_b32 m0, s41
	s_addc_u32 s49, s27, 0
	global_load_lds_dwordx4 v[222:223], off
	v_lshl_add_u64 v[224:225], s[48:49], 0, v[130:131]
	s_mov_b32 m0, s42
	v_lshl_add_u64 v[226:227], s[36:37], 0, v[132:133]
	global_load_lds_dwordx4 v[224:225], off
	v_lshl_add_u64 v[224:225], s[48:49], 0, v[134:135]
	s_mov_b32 m0, s43
	s_nop 0
	global_load_lds_dwordx4 v[224:225], off
	v_lshl_add_u64 v[224:225], s[36:37], 0, v[128:129]
	s_mov_b32 m0, s3
	s_nop 0
	global_load_lds_dwordx4 v[224:225], off
	s_mov_b32 m0, s5
	s_nop 0
	global_load_lds_dwordx4 v[226:227], off
	s_waitcnt vmcnt(8)
	s_waitcnt lgkmcnt(0)
	s_barrier
	s_setprio 1
	s_waitcnt lgkmcnt(0)
	v_mfma_f32_16x16x32_bf16 v[60:63], v[152:155], v[188:191], v[60:63]
	v_mfma_f32_16x16x32_bf16 v[56:59], v[160:163], v[188:191], v[56:59]
	v_mfma_f32_16x16x32_bf16 v[44:47], v[152:155], v[196:199], v[44:47]
	v_mfma_f32_16x16x32_bf16 v[40:43], v[160:163], v[196:199], v[40:43]
	v_mfma_f32_16x16x32_bf16 v[28:31], v[152:155], v[204:207], v[28:31]
	v_mfma_f32_16x16x32_bf16 v[24:27], v[160:163], v[204:207], v[24:27]
	v_mfma_f32_16x16x32_bf16 v[12:15], v[152:155], v[212:215], v[12:15]
	v_mfma_f32_16x16x32_bf16 v[8:11], v[160:163], v[212:215], v[8:11]
	v_mfma_f32_16x16x32_bf16 v[60:63], v[156:159], v[192:195], v[60:63]
	v_mfma_f32_16x16x32_bf16 v[56:59], v[168:171], v[192:195], v[56:59]
	v_mfma_f32_16x16x32_bf16 v[44:47], v[156:159], v[200:203], v[44:47]
	v_mfma_f32_16x16x32_bf16 v[40:43], v[168:171], v[200:203], v[40:43]
	v_mfma_f32_16x16x32_bf16 v[28:31], v[156:159], v[208:211], v[28:31]
	v_mfma_f32_16x16x32_bf16 v[24:27], v[168:171], v[208:211], v[24:27]
	v_mfma_f32_16x16x32_bf16 v[12:15], v[156:159], v[216:219], v[12:15]
	v_mfma_f32_16x16x32_bf16 v[8:11], v[168:171], v[216:219], v[8:11]
	v_mfma_f32_16x16x32_bf16 v[52:55], v[172:175], v[188:191], v[52:55]
	v_mfma_f32_16x16x32_bf16 v[48:51], v[180:183], v[188:191], v[48:51]
	v_mfma_f32_16x16x32_bf16 v[36:39], v[172:175], v[196:199], v[36:39]
	v_mfma_f32_16x16x32_bf16 v[32:35], v[180:183], v[196:199], v[32:35]
	v_mfma_f32_16x16x32_bf16 v[20:23], v[172:175], v[204:207], v[20:23]
	v_mfma_f32_16x16x32_bf16 v[16:19], v[180:183], v[204:207], v[16:19]
	v_mfma_f32_16x16x32_bf16 v[4:7], v[172:175], v[212:215], v[4:7]
	v_mfma_f32_16x16x32_bf16 v[0:3], v[180:183], v[212:215], v[0:3]
	v_mfma_f32_16x16x32_bf16 v[52:55], v[176:179], v[192:195], v[52:55]
	v_mfma_f32_16x16x32_bf16 v[48:51], v[184:187], v[192:195], v[48:51]
	v_mfma_f32_16x16x32_bf16 v[36:39], v[176:179], v[200:203], v[36:39]
	v_mfma_f32_16x16x32_bf16 v[32:35], v[184:187], v[200:203], v[32:35]
	v_mfma_f32_16x16x32_bf16 v[20:23], v[176:179], v[208:211], v[20:23]
	v_mfma_f32_16x16x32_bf16 v[16:19], v[184:187], v[208:211], v[16:19]
	v_mfma_f32_16x16x32_bf16 v[4:7], v[176:179], v[216:219], v[4:7]
	v_mfma_f32_16x16x32_bf16 v[0:3], v[184:187], v[216:219], v[0:3]
	s_setprio 0
	s_barrier
	ds_read_b128 v[152:155], v148
	ds_read_b128 v[156:159], v148 offset:1024
	ds_read_b128 v[160:163], v148 offset:2048
	ds_read_b128 v[168:171], v148 offset:3072
	ds_read_b128 v[172:175], v150
	ds_read_b128 v[176:179], v150 offset:1024
	ds_read_b128 v[180:183], v150 offset:2048
	ds_read_b128 v[184:187], v150 offset:3072
	s_add_u32 s36, s36, 0x40000
	s_addc_u32 s37, s37, 0
	s_mov_b32 m0, s13
	v_lshl_add_u64 v[228:229], s[36:37], 0, v[128:129]
	ds_read_b128 v[188:191], v147 offset:32768
	ds_read_b128 v[192:195], v147 offset:33792
	ds_read_b128 v[196:199], v147 offset:34816
	ds_read_b128 v[200:203], v147 offset:35840
	ds_read_b128 v[204:207], v147 offset:36864
	ds_read_b128 v[208:211], v147 offset:37888
	ds_read_b128 v[212:215], v147 offset:38912
	ds_read_b128 v[216:219], v147 offset:39936
	global_load_lds_dwordx4 v[228:229], off
	v_lshl_add_u64 v[228:229], s[36:37], 0, v[132:133]
	s_mov_b32 m0, s15
	s_nop 0
	global_load_lds_dwordx4 v[228:229], off
	s_waitcnt vmcnt(8)
	s_waitcnt lgkmcnt(0)
	s_barrier
	s_setprio 1
	s_waitcnt lgkmcnt(0)
	v_mfma_f32_16x16x32_bf16 v[124:127], v[152:155], v[188:191], v[124:127]
	v_mfma_f32_16x16x32_bf16 v[120:123], v[160:163], v[188:191], v[120:123]
	v_mfma_f32_16x16x32_bf16 v[108:111], v[152:155], v[196:199], v[108:111]
	v_mfma_f32_16x16x32_bf16 v[104:107], v[160:163], v[196:199], v[104:107]
	v_mfma_f32_16x16x32_bf16 v[92:95], v[152:155], v[204:207], v[92:95]
	v_mfma_f32_16x16x32_bf16 v[88:91], v[160:163], v[204:207], v[88:91]
	v_mfma_f32_16x16x32_bf16 v[76:79], v[152:155], v[212:215], v[76:79]
	v_mfma_f32_16x16x32_bf16 v[72:75], v[160:163], v[212:215], v[72:75]
	v_mfma_f32_16x16x32_bf16 v[124:127], v[156:159], v[192:195], v[124:127]
	v_mfma_f32_16x16x32_bf16 v[120:123], v[168:171], v[192:195], v[120:123]
	v_mfma_f32_16x16x32_bf16 v[108:111], v[156:159], v[200:203], v[108:111]
	v_mfma_f32_16x16x32_bf16 v[104:107], v[168:171], v[200:203], v[104:107]
	v_mfma_f32_16x16x32_bf16 v[92:95], v[156:159], v[208:211], v[92:95]
	v_mfma_f32_16x16x32_bf16 v[88:91], v[168:171], v[208:211], v[88:91]
	v_mfma_f32_16x16x32_bf16 v[76:79], v[156:159], v[216:219], v[76:79]
	v_mfma_f32_16x16x32_bf16 v[72:75], v[168:171], v[216:219], v[72:75]
	v_mfma_f32_16x16x32_bf16 v[116:119], v[172:175], v[188:191], v[116:119]
	v_mfma_f32_16x16x32_bf16 v[112:115], v[180:183], v[188:191], v[112:115]
	v_mfma_f32_16x16x32_bf16 v[100:103], v[172:175], v[196:199], v[100:103]
	v_mfma_f32_16x16x32_bf16 v[96:99], v[180:183], v[196:199], v[96:99]
	v_mfma_f32_16x16x32_bf16 v[84:87], v[172:175], v[204:207], v[84:87]
	v_mfma_f32_16x16x32_bf16 v[80:83], v[180:183], v[204:207], v[80:83]
	v_mfma_f32_16x16x32_bf16 v[68:71], v[172:175], v[212:215], v[68:71]
	v_mfma_f32_16x16x32_bf16 v[64:67], v[180:183], v[212:215], v[64:67]
	v_mfma_f32_16x16x32_bf16 v[116:119], v[176:179], v[192:195], v[116:119]
	v_mfma_f32_16x16x32_bf16 v[112:115], v[184:187], v[192:195], v[112:115]
	v_mfma_f32_16x16x32_bf16 v[100:103], v[176:179], v[200:203], v[100:103]
	v_mfma_f32_16x16x32_bf16 v[96:99], v[184:187], v[200:203], v[96:99]
	v_mfma_f32_16x16x32_bf16 v[84:87], v[176:179], v[208:211], v[84:87]
	v_mfma_f32_16x16x32_bf16 v[80:83], v[184:187], v[208:211], v[80:83]
	v_mfma_f32_16x16x32_bf16 v[68:71], v[176:179], v[216:219], v[68:71]
	v_mfma_f32_16x16x32_bf16 v[64:67], v[184:187], v[216:219], v[64:67]
	s_setprio 0
	s_barrier
	s_mov_b32 m0, s44
	v_lshl_add_u64 v[220:221], v[220:221], 0, s[10:11]
	s_add_u32 s26, s26, 0x40080
	ds_read_b128 v[188:191], v147 offset:49152
	ds_read_b128 v[192:195], v147 offset:50176
	ds_read_b128 v[196:199], v147 offset:51200
	ds_read_b128 v[200:203], v147 offset:52224
	ds_read_b128 v[204:207], v147 offset:53248
	ds_read_b128 v[208:211], v147 offset:54272
	ds_read_b128 v[212:215], v147 offset:55296
	ds_read_b128 v[216:219], v147 offset:56320
	global_load_lds_dwordx4 v[220:221], off
	v_lshl_add_u64 v[220:221], v[222:223], 0, s[10:11]
	s_mov_b32 m0, s45
	s_addc_u32 s27, s27, 0
	global_load_lds_dwordx4 v[220:221], off
	v_lshl_add_u64 v[220:221], s[26:27], 0, v[130:131]
	s_mov_b32 m0, s46
	s_nop 0
	global_load_lds_dwordx4 v[220:221], off
	v_lshl_add_u64 v[220:221], s[26:27], 0, v[134:135]
	s_mov_b32 m0, s47
	s_nop 0
	global_load_lds_dwordx4 v[220:221], off
	v_lshl_add_u64 v[220:221], v[224:225], 0, s[10:11]
	s_mov_b32 m0, s19
	s_nop 0
	global_load_lds_dwordx4 v[220:221], off
	v_lshl_add_u64 v[220:221], v[226:227], 0, s[10:11]
	s_mov_b32 m0, s33
	s_nop 0
	global_load_lds_dwordx4 v[220:221], off
	s_waitcnt vmcnt(8)
	s_waitcnt lgkmcnt(0)
	s_barrier
	s_setprio 1
	s_waitcnt lgkmcnt(0)
	v_mfma_f32_16x16x32_bf16 v[60:63], v[152:155], v[188:191], v[60:63]
	v_mfma_f32_16x16x32_bf16 v[56:59], v[160:163], v[188:191], v[56:59]
	v_mfma_f32_16x16x32_bf16 v[44:47], v[152:155], v[196:199], v[44:47]
	v_mfma_f32_16x16x32_bf16 v[40:43], v[160:163], v[196:199], v[40:43]
	v_mfma_f32_16x16x32_bf16 v[28:31], v[152:155], v[204:207], v[28:31]
	v_mfma_f32_16x16x32_bf16 v[24:27], v[160:163], v[204:207], v[24:27]
	v_mfma_f32_16x16x32_bf16 v[12:15], v[152:155], v[212:215], v[12:15]
	v_mfma_f32_16x16x32_bf16 v[8:11], v[160:163], v[212:215], v[8:11]
	v_mfma_f32_16x16x32_bf16 v[60:63], v[156:159], v[192:195], v[60:63]
	v_mfma_f32_16x16x32_bf16 v[56:59], v[168:171], v[192:195], v[56:59]
	v_mfma_f32_16x16x32_bf16 v[44:47], v[156:159], v[200:203], v[44:47]
	v_mfma_f32_16x16x32_bf16 v[40:43], v[168:171], v[200:203], v[40:43]
	v_mfma_f32_16x16x32_bf16 v[28:31], v[156:159], v[208:211], v[28:31]
	v_mfma_f32_16x16x32_bf16 v[24:27], v[168:171], v[208:211], v[24:27]
	v_mfma_f32_16x16x32_bf16 v[12:15], v[156:159], v[216:219], v[12:15]
	v_mfma_f32_16x16x32_bf16 v[8:11], v[168:171], v[216:219], v[8:11]
	v_mfma_f32_16x16x32_bf16 v[52:55], v[172:175], v[188:191], v[52:55]
	v_mfma_f32_16x16x32_bf16 v[48:51], v[180:183], v[188:191], v[48:51]
	v_mfma_f32_16x16x32_bf16 v[36:39], v[172:175], v[196:199], v[36:39]
	v_mfma_f32_16x16x32_bf16 v[32:35], v[180:183], v[196:199], v[32:35]
	v_mfma_f32_16x16x32_bf16 v[20:23], v[172:175], v[204:207], v[20:23]
	v_mfma_f32_16x16x32_bf16 v[16:19], v[180:183], v[204:207], v[16:19]
	v_mfma_f32_16x16x32_bf16 v[4:7], v[172:175], v[212:215], v[4:7]
	v_mfma_f32_16x16x32_bf16 v[0:3], v[180:183], v[212:215], v[0:3]
	v_mfma_f32_16x16x32_bf16 v[52:55], v[176:179], v[192:195], v[52:55]
	v_mfma_f32_16x16x32_bf16 v[48:51], v[184:187], v[192:195], v[48:51]
	v_mfma_f32_16x16x32_bf16 v[36:39], v[176:179], v[200:203], v[36:39]
	v_mfma_f32_16x16x32_bf16 v[32:35], v[184:187], v[200:203], v[32:35]
	v_mfma_f32_16x16x32_bf16 v[20:23], v[176:179], v[208:211], v[20:23]
	v_mfma_f32_16x16x32_bf16 v[16:19], v[184:187], v[208:211], v[16:19]
	v_mfma_f32_16x16x32_bf16 v[4:7], v[176:179], v[216:219], v[4:7]
	v_mfma_f32_16x16x32_bf16 v[0:3], v[184:187], v[216:219], v[0:3]
	s_setprio 0
	s_barrier
	s_add_i32 s34, s34, 2
	s_add_u32 s24, s24, 0x100
	s_addc_u32 s25, s25, 0
	s_cmp_gt_u32 s34, 13
	s_cbranch_scc0 .LBB0_131
	s_cmpk_lt_u32 s2, 0x100
	s_cbranch_scc0 .LBB0_134
	s_barrier

.LBB0_681:
	ds_read_b128 v[128:131], v174
	ds_read_b128 v[132:135], v174 offset:1024
	ds_read_b128 v[160:163], v174 offset:2048
	ds_read_b128 v[178:181], v174 offset:3072
	ds_read_b128 v[182:185], v175
	ds_read_b128 v[186:189], v175 offset:1024
	ds_read_b128 v[190:193], v175 offset:2048
	ds_read_b128 v[194:197], v175 offset:3072
	s_add_u32 s10, s8, 0xfffc0080
	s_addc_u32 s11, s9, -1
	s_cmp_eq_u32 s48, 12
	s_cselect_b32 s13, s2, s11
	s_cselect_b32 s12, s7, s10
	s_cselect_b32 s11, s24, s42
	s_cselect_b32 s10, s33, s34
	v_lshl_add_u64 v[230:231], s[8:9], 0, v[152:153]
	s_add_i32 m0, s41, 0xc000
	ds_read_b128 v[198:201], v176
	ds_read_b128 v[202:205], v176 offset:1024
	ds_read_b128 v[206:209], v176 offset:2048
	ds_read_b128 v[210:213], v176 offset:3072
	ds_read_b128 v[214:217], v176 offset:4096
	ds_read_b128 v[218:221], v176 offset:5120
	ds_read_b128 v[222:225], v176 offset:6144
	ds_read_b128 v[226:229], v176 offset:7168
	global_load_lds_dwordx4 v[230:231], off
	v_lshl_add_u64 v[230:231], s[8:9], 0, v[154:155]
	s_add_i32 m0, s41, 0xe000
	s_nop 0
	global_load_lds_dwordx4 v[230:231], off
	s_waitcnt vmcnt(8)
	s_waitcnt lgkmcnt(0)
	s_barrier
	s_setprio 1
	s_waitcnt lgkmcnt(0)
	v_mfma_f32_16x16x32_bf16 v[124:127], v[128:131], v[198:201], v[124:127]
	v_mfma_f32_16x16x32_bf16 v[120:123], v[160:163], v[198:201], v[120:123]
	v_mfma_f32_16x16x32_bf16 v[108:111], v[128:131], v[206:209], v[108:111]
	v_mfma_f32_16x16x32_bf16 v[104:107], v[160:163], v[206:209], v[104:107]
	v_mfma_f32_16x16x32_bf16 v[92:95], v[128:131], v[214:217], v[92:95]
	v_mfma_f32_16x16x32_bf16 v[88:91], v[160:163], v[214:217], v[88:91]
	v_mfma_f32_16x16x32_bf16 v[76:79], v[128:131], v[222:225], v[76:79]
	v_mfma_f32_16x16x32_bf16 v[72:75], v[160:163], v[222:225], v[72:75]
	v_mfma_f32_16x16x32_bf16 v[124:127], v[132:135], v[202:205], v[124:127]
	v_mfma_f32_16x16x32_bf16 v[120:123], v[178:181], v[202:205], v[120:123]
	v_mfma_f32_16x16x32_bf16 v[108:111], v[132:135], v[210:213], v[108:111]
	v_mfma_f32_16x16x32_bf16 v[104:107], v[178:181], v[210:213], v[104:107]
	v_mfma_f32_16x16x32_bf16 v[92:95], v[132:135], v[218:221], v[92:95]
	v_mfma_f32_16x16x32_bf16 v[88:91], v[178:181], v[218:221], v[88:91]
	v_mfma_f32_16x16x32_bf16 v[76:79], v[132:135], v[226:229], v[76:79]
	v_mfma_f32_16x16x32_bf16 v[72:75], v[178:181], v[226:229], v[72:75]
	v_mfma_f32_16x16x32_bf16 v[116:119], v[182:185], v[198:201], v[116:119]
	v_mfma_f32_16x16x32_bf16 v[112:115], v[190:193], v[198:201], v[112:115]
	v_mfma_f32_16x16x32_bf16 v[100:103], v[182:185], v[206:209], v[100:103]
	v_mfma_f32_16x16x32_bf16 v[96:99], v[190:193], v[206:209], v[96:99]
	v_mfma_f32_16x16x32_bf16 v[84:87], v[182:185], v[214:217], v[84:87]
	v_mfma_f32_16x16x32_bf16 v[80:83], v[190:193], v[214:217], v[80:83]
	v_mfma_f32_16x16x32_bf16 v[68:71], v[182:185], v[222:225], v[68:71]
	v_mfma_f32_16x16x32_bf16 v[64:67], v[190:193], v[222:225], v[64:67]
	v_mfma_f32_16x16x32_bf16 v[116:119], v[186:189], v[202:205], v[116:119]
	v_mfma_f32_16x16x32_bf16 v[112:115], v[194:197], v[202:205], v[112:115]
	v_mfma_f32_16x16x32_bf16 v[100:103], v[186:189], v[210:213], v[100:103]
	v_mfma_f32_16x16x32_bf16 v[96:99], v[194:197], v[210:213], v[96:99]
	v_mfma_f32_16x16x32_bf16 v[84:87], v[186:189], v[218:221], v[84:87]
	v_mfma_f32_16x16x32_bf16 v[80:83], v[194:197], v[218:221], v[80:83]
	v_mfma_f32_16x16x32_bf16 v[68:71], v[186:189], v[226:229], v[68:71]
	v_mfma_f32_16x16x32_bf16 v[64:67], v[194:197], v[226:229], v[64:67]
	s_setprio 0
	s_barrier
	s_add_i32 s49, s94, s35
	v_lshl_add_u64 v[230:231], s[10:11], 0, v[142:143]
	s_mov_b32 m0, s49
	ds_read_b128 v[198:201], v176 offset:16384
	ds_read_b128 v[202:205], v176 offset:17408
	ds_read_b128 v[206:209], v176 offset:18432
	ds_read_b128 v[210:213], v176 offset:19456
	ds_read_b128 v[214:217], v176 offset:20480
	ds_read_b128 v[218:221], v176 offset:21504
	ds_read_b128 v[222:225], v176 offset:22528
	ds_read_b128 v[226:229], v176 offset:23552
	global_load_lds_dwordx4 v[230:231], off
	s_add_i32 m0, s49, 0x2000
	s_add_u32 s50, s10, 0x40000
	v_lshl_add_u64 v[232:233], s[10:11], 0, v[146:147]
	s_addc_u32 s51, s11, 0
	s_add_i32 s49, s95, s35
	global_load_lds_dwordx4 v[232:233], off
	v_lshl_add_u64 v[234:235], s[50:51], 0, v[142:143]
	s_mov_b32 m0, s49
	v_lshl_add_u64 v[236:237], s[12:13], 0, v[144:145]
	global_load_lds_dwordx4 v[234:235], off
	v_lshl_add_u64 v[234:235], s[50:51], 0, v[146:147]
	s_add_i32 m0, s49, 0x2000
	s_nop 0
	global_load_lds_dwordx4 v[234:235], off
	v_lshl_add_u64 v[234:235], s[12:13], 0, v[140:141]
	s_mov_b32 m0, s41
	s_nop 0
	global_load_lds_dwordx4 v[234:235], off
	s_mov_b32 m0, s55
	s_nop 0
	global_load_lds_dwordx4 v[236:237], off
	s_waitcnt vmcnt(8)
	s_waitcnt lgkmcnt(0)
	s_barrier
	s_setprio 1
	s_waitcnt lgkmcnt(0)
	v_mfma_f32_16x16x32_bf16 v[60:63], v[128:131], v[198:201], v[60:63]
	v_mfma_f32_16x16x32_bf16 v[56:59], v[160:163], v[198:201], v[56:59]
	v_mfma_f32_16x16x32_bf16 v[44:47], v[128:131], v[206:209], v[44:47]
	v_mfma_f32_16x16x32_bf16 v[40:43], v[160:163], v[206:209], v[40:43]
	v_mfma_f32_16x16x32_bf16 v[28:31], v[128:131], v[214:217], v[28:31]
	v_mfma_f32_16x16x32_bf16 v[24:27], v[160:163], v[214:217], v[24:27]
	v_mfma_f32_16x16x32_bf16 v[12:15], v[128:131], v[222:225], v[12:15]
	v_mfma_f32_16x16x32_bf16 v[8:11], v[160:163], v[222:225], v[8:11]
	v_mfma_f32_16x16x32_bf16 v[60:63], v[132:135], v[202:205], v[60:63]
	v_mfma_f32_16x16x32_bf16 v[56:59], v[178:181], v[202:205], v[56:59]
	v_mfma_f32_16x16x32_bf16 v[44:47], v[132:135], v[210:213], v[44:47]
	v_mfma_f32_16x16x32_bf16 v[40:43], v[178:181], v[210:213], v[40:43]
	v_mfma_f32_16x16x32_bf16 v[28:31], v[132:135], v[218:221], v[28:31]
	v_mfma_f32_16x16x32_bf16 v[24:27], v[178:181], v[218:221], v[24:27]
	v_mfma_f32_16x16x32_bf16 v[12:15], v[132:135], v[226:229], v[12:15]
	v_mfma_f32_16x16x32_bf16 v[8:11], v[178:181], v[226:229], v[8:11]
	v_mfma_f32_16x16x32_bf16 v[52:55], v[182:185], v[198:201], v[52:55]
	v_mfma_f32_16x16x32_bf16 v[48:51], v[190:193], v[198:201], v[48:51]
	v_mfma_f32_16x16x32_bf16 v[36:39], v[182:185], v[206:209], v[36:39]
	v_mfma_f32_16x16x32_bf16 v[32:35], v[190:193], v[206:209], v[32:35]
	v_mfma_f32_16x16x32_bf16 v[20:23], v[182:185], v[214:217], v[20:23]
	v_mfma_f32_16x16x32_bf16 v[16:19], v[190:193], v[214:217], v[16:19]
	v_mfma_f32_16x16x32_bf16 v[4:7], v[182:185], v[222:225], v[4:7]
	v_mfma_f32_16x16x32_bf16 v[0:3], v[190:193], v[222:225], v[0:3]
	v_mfma_f32_16x16x32_bf16 v[52:55], v[186:189], v[202:205], v[52:55]
	v_mfma_f32_16x16x32_bf16 v[48:51], v[194:197], v[202:205], v[48:51]
	v_mfma_f32_16x16x32_bf16 v[36:39], v[186:189], v[210:213], v[36:39]
	v_mfma_f32_16x16x32_bf16 v[32:35], v[194:197], v[210:213], v[32:35]
	v_mfma_f32_16x16x32_bf16 v[20:23], v[186:189], v[218:221], v[20:23]
	v_mfma_f32_16x16x32_bf16 v[16:19], v[194:197], v[218:221], v[16:19]
	v_mfma_f32_16x16x32_bf16 v[4:7], v[186:189], v[226:229], v[4:7]
	v_mfma_f32_16x16x32_bf16 v[0:3], v[194:197], v[226:229], v[0:3]
	s_setprio 0
	s_barrier
	s_add_i32 s49, 0, 0x18000
	v_add_u32_e32 v148, s49, v167
	s_add_i32 s50, 0, 0x1c000
	ds_read_b128 v[128:131], v148
	ds_read_b128 v[132:135], v148 offset:1024
	ds_read_b128 v[160:163], v148 offset:2048
	ds_read_b128 v[178:181], v148 offset:3072
	v_add_u32_e32 v148, s50, v167
	ds_read_b128 v[182:185], v148
	ds_read_b128 v[186:189], v148 offset:1024
	ds_read_b128 v[190:193], v148 offset:2048
	ds_read_b128 v[194:197], v148 offset:3072
	s_add_u32 s12, s12, 0x40000
	s_addc_u32 s13, s13, 0
	s_mov_b32 m0, s59
	v_lshl_add_u64 v[238:239], s[12:13], 0, v[140:141]
	ds_read_b128 v[198:201], v176 offset:32768
	ds_read_b128 v[202:205], v176 offset:33792
	ds_read_b128 v[206:209], v176 offset:34816
	ds_read_b128 v[210:213], v176 offset:35840
	ds_read_b128 v[214:217], v176 offset:36864
	ds_read_b128 v[218:221], v176 offset:37888
	ds_read_b128 v[222:225], v176 offset:38912
	ds_read_b128 v[226:229], v176 offset:39936
	global_load_lds_dwordx4 v[238:239], off
	v_lshl_add_u64 v[238:239], s[12:13], 0, v[144:145]
	s_mov_b32 m0, s61
	s_nop 0
	global_load_lds_dwordx4 v[238:239], off
	s_waitcnt vmcnt(8)
	s_waitcnt lgkmcnt(0)
	s_barrier
	s_setprio 1
	s_waitcnt lgkmcnt(0)
	v_mfma_f32_16x16x32_bf16 v[124:127], v[128:131], v[198:201], v[124:127]
	v_mfma_f32_16x16x32_bf16 v[120:123], v[160:163], v[198:201], v[120:123]
	v_mfma_f32_16x16x32_bf16 v[108:111], v[128:131], v[206:209], v[108:111]
	v_mfma_f32_16x16x32_bf16 v[104:107], v[160:163], v[206:209], v[104:107]
	v_mfma_f32_16x16x32_bf16 v[92:95], v[128:131], v[214:217], v[92:95]
	v_mfma_f32_16x16x32_bf16 v[88:91], v[160:163], v[214:217], v[88:91]
	v_mfma_f32_16x16x32_bf16 v[76:79], v[128:131], v[222:225], v[76:79]
	v_mfma_f32_16x16x32_bf16 v[72:75], v[160:163], v[222:225], v[72:75]
	v_mfma_f32_16x16x32_bf16 v[124:127], v[132:135], v[202:205], v[124:127]
	v_mfma_f32_16x16x32_bf16 v[120:123], v[178:181], v[202:205], v[120:123]
	v_mfma_f32_16x16x32_bf16 v[108:111], v[132:135], v[210:213], v[108:111]
	v_mfma_f32_16x16x32_bf16 v[104:107], v[178:181], v[210:213], v[104:107]
	v_mfma_f32_16x16x32_bf16 v[92:95], v[132:135], v[218:221], v[92:95]
	v_mfma_f32_16x16x32_bf16 v[88:91], v[178:181], v[218:221], v[88:91]
	v_mfma_f32_16x16x32_bf16 v[76:79], v[132:135], v[226:229], v[76:79]
	v_mfma_f32_16x16x32_bf16 v[72:75], v[178:181], v[226:229], v[72:75]
	v_mfma_f32_16x16x32_bf16 v[116:119], v[182:185], v[198:201], v[116:119]
	v_mfma_f32_16x16x32_bf16 v[112:115], v[190:193], v[198:201], v[112:115]
	v_mfma_f32_16x16x32_bf16 v[100:103], v[182:185], v[206:209], v[100:103]
	v_mfma_f32_16x16x32_bf16 v[96:99], v[190:193], v[206:209], v[96:99]
	v_mfma_f32_16x16x32_bf16 v[84:87], v[182:185], v[214:217], v[84:87]
	v_mfma_f32_16x16x32_bf16 v[80:83], v[190:193], v[214:217], v[80:83]
	v_mfma_f32_16x16x32_bf16 v[68:71], v[182:185], v[222:225], v[68:71]
	v_mfma_f32_16x16x32_bf16 v[64:67], v[190:193], v[222:225], v[64:67]
	v_mfma_f32_16x16x32_bf16 v[116:119], v[186:189], v[202:205], v[116:119]
	v_mfma_f32_16x16x32_bf16 v[112:115], v[194:197], v[202:205], v[112:115]
	v_mfma_f32_16x16x32_bf16 v[100:103], v[186:189], v[210:213], v[100:103]
	v_mfma_f32_16x16x32_bf16 v[96:99], v[194:197], v[210:213], v[96:99]
	v_mfma_f32_16x16x32_bf16 v[84:87], v[186:189], v[218:221], v[84:87]
	v_mfma_f32_16x16x32_bf16 v[80:83], v[194:197], v[218:221], v[80:83]
	v_mfma_f32_16x16x32_bf16 v[68:71], v[186:189], v[226:229], v[68:71]
	v_mfma_f32_16x16x32_bf16 v[64:67], v[194:197], v[226:229], v[64:67]
	s_setprio 0
	s_barrier
	s_add_i32 s12, s49, s35
	v_lshl_add_u64 v[230:231], v[230:231], 0, s[36:37]
	s_mov_b32 m0, s12
	ds_read_b128 v[198:201], v176 offset:49152
	ds_read_b128 v[202:205], v176 offset:50176
	ds_read_b128 v[206:209], v176 offset:51200
	ds_read_b128 v[210:213], v176 offset:52224
	ds_read_b128 v[214:217], v176 offset:53248
	ds_read_b128 v[218:221], v176 offset:54272
	ds_read_b128 v[222:225], v176 offset:55296
	ds_read_b128 v[226:229], v176 offset:56320
	global_load_lds_dwordx4 v[230:231], off
	s_add_i32 m0, s12, 0x2000
	s_add_u32 s10, s10, 0x40080
	v_lshl_add_u64 v[230:231], v[232:233], 0, s[36:37]
	s_addc_u32 s11, s11, 0
	s_add_i32 s12, s50, s35
	global_load_lds_dwordx4 v[230:231], off
	v_lshl_add_u64 v[230:231], s[10:11], 0, v[142:143]
	s_mov_b32 m0, s12
	s_nop 0
	global_load_lds_dwordx4 v[230:231], off
	v_lshl_add_u64 v[230:231], s[10:11], 0, v[146:147]
	s_add_i32 m0, s12, 0x2000
	s_nop 0
	global_load_lds_dwordx4 v[230:231], off
	v_lshl_add_u64 v[230:231], v[234:235], 0, s[36:37]
	s_mov_b32 m0, s82
	s_nop 0
	global_load_lds_dwordx4 v[230:231], off
	v_lshl_add_u64 v[230:231], v[236:237], 0, s[36:37]
	s_mov_b32 m0, s83
	s_nop 0
	global_load_lds_dwordx4 v[230:231], off
	s_waitcnt vmcnt(8)
	s_waitcnt lgkmcnt(0)
	s_barrier
	s_setprio 1
	s_waitcnt lgkmcnt(0)
	v_mfma_f32_16x16x32_bf16 v[60:63], v[128:131], v[198:201], v[60:63]
	v_mfma_f32_16x16x32_bf16 v[56:59], v[160:163], v[198:201], v[56:59]
	v_mfma_f32_16x16x32_bf16 v[44:47], v[128:131], v[206:209], v[44:47]
	v_mfma_f32_16x16x32_bf16 v[40:43], v[160:163], v[206:209], v[40:43]
	v_mfma_f32_16x16x32_bf16 v[28:31], v[128:131], v[214:217], v[28:31]
	v_mfma_f32_16x16x32_bf16 v[24:27], v[160:163], v[214:217], v[24:27]
	v_mfma_f32_16x16x32_bf16 v[12:15], v[128:131], v[222:225], v[12:15]
	v_mfma_f32_16x16x32_bf16 v[8:11], v[160:163], v[222:225], v[8:11]
	v_mfma_f32_16x16x32_bf16 v[60:63], v[132:135], v[202:205], v[60:63]
	v_mfma_f32_16x16x32_bf16 v[56:59], v[178:181], v[202:205], v[56:59]
	v_mfma_f32_16x16x32_bf16 v[44:47], v[132:135], v[210:213], v[44:47]
	v_mfma_f32_16x16x32_bf16 v[40:43], v[178:181], v[210:213], v[40:43]
	v_mfma_f32_16x16x32_bf16 v[28:31], v[132:135], v[218:221], v[28:31]
	v_mfma_f32_16x16x32_bf16 v[24:27], v[178:181], v[218:221], v[24:27]
	v_mfma_f32_16x16x32_bf16 v[12:15], v[132:135], v[226:229], v[12:15]
	v_mfma_f32_16x16x32_bf16 v[8:11], v[178:181], v[226:229], v[8:11]
	v_mfma_f32_16x16x32_bf16 v[52:55], v[182:185], v[198:201], v[52:55]
	v_mfma_f32_16x16x32_bf16 v[48:51], v[190:193], v[198:201], v[48:51]
	v_mfma_f32_16x16x32_bf16 v[36:39], v[182:185], v[206:209], v[36:39]
	v_mfma_f32_16x16x32_bf16 v[32:35], v[190:193], v[206:209], v[32:35]
	v_mfma_f32_16x16x32_bf16 v[20:23], v[182:185], v[214:217], v[20:23]
	v_mfma_f32_16x16x32_bf16 v[16:19], v[190:193], v[214:217], v[16:19]
	v_mfma_f32_16x16x32_bf16 v[4:7], v[182:185], v[222:225], v[4:7]
	v_mfma_f32_16x16x32_bf16 v[0:3], v[190:193], v[222:225], v[0:3]
	v_mfma_f32_16x16x32_bf16 v[52:55], v[186:189], v[202:205], v[52:55]
	v_mfma_f32_16x16x32_bf16 v[48:51], v[194:197], v[202:205], v[48:51]
	v_mfma_f32_16x16x32_bf16 v[36:39], v[186:189], v[210:213], v[36:39]
	v_mfma_f32_16x16x32_bf16 v[32:35], v[194:197], v[210:213], v[32:35]
	v_mfma_f32_16x16x32_bf16 v[20:23], v[186:189], v[218:221], v[20:23]
	v_mfma_f32_16x16x32_bf16 v[16:19], v[194:197], v[218:221], v[16:19]
	v_mfma_f32_16x16x32_bf16 v[4:7], v[186:189], v[226:229], v[4:7]
	v_mfma_f32_16x16x32_bf16 v[0:3], v[194:197], v[226:229], v[0:3]
	s_setprio 0
	s_barrier
	s_add_i32 s48, s48, 2
	s_add_u32 s8, s8, 0x100
	s_addc_u32 s9, s9, 0
	s_add_u32 s34, s34, 0x100
	s_addc_u32 s42, s42, 0
	s_cmp_gt_u32 s48, 13
	s_cbranch_scc0 .LBB0_681
	s_and_b64 vcc, exec, s[38:39]
	s_cbranch_vccz .LBB0_684
	s_barrier

.LBB0_1506:
	ds_read_b128 v[166:169], v159
	ds_read_b128 v[170:173], v159 offset:1024
	ds_read_b128 v[174:177], v159 offset:2048
	ds_read_b128 v[178:181], v159 offset:3072
	ds_read_b128 v[182:185], v160
	ds_read_b128 v[186:189], v160 offset:1024
	ds_read_b128 v[190:193], v160 offset:2048
	ds_read_b128 v[194:197], v160 offset:3072
	s_add_i32 s49, s48, 2
	s_add_u32 s50, s68, 0xfffc0080
	s_addc_u32 s51, s69, -1
	s_cmp_eq_u32 s33, s48
	s_cselect_b32 s73, s61, s51
	s_cselect_b32 s72, s60, s50
	s_cselect_b32 s71, s63, s42
	s_cselect_b32 s70, s62, s34
	v_lshl_add_u64 v[146:147], s[68:69], 0, v[142:143]
	s_add_i32 m0, s14, 0xc000
	ds_read_b128 v[198:201], v161
	ds_read_b128 v[202:205], v161 offset:1024
	ds_read_b128 v[206:209], v161 offset:2048
	ds_read_b128 v[210:213], v161 offset:3072
	ds_read_b128 v[214:217], v161 offset:4096
	ds_read_b128 v[218:221], v161 offset:5120
	ds_read_b128 v[222:225], v161 offset:6144
	ds_read_b128 v[226:229], v161 offset:7168
	global_load_lds_dwordx4 v[146:147], off
	v_lshl_add_u64 v[146:147], s[68:69], 0, v[144:145]
	s_add_i32 m0, s14, 0xe000
	s_nop 0
	global_load_lds_dwordx4 v[146:147], off
	s_waitcnt vmcnt(8)
	s_waitcnt lgkmcnt(0)
	s_barrier
	s_setprio 1
	s_waitcnt lgkmcnt(0)
	v_mfma_f32_16x16x32_bf16 v[124:127], v[166:169], v[198:201], v[124:127]
	v_mfma_f32_16x16x32_bf16 v[120:123], v[174:177], v[198:201], v[120:123]
	v_mfma_f32_16x16x32_bf16 v[108:111], v[166:169], v[206:209], v[108:111]
	v_mfma_f32_16x16x32_bf16 v[104:107], v[174:177], v[206:209], v[104:107]
	v_mfma_f32_16x16x32_bf16 v[92:95], v[166:169], v[214:217], v[92:95]
	v_mfma_f32_16x16x32_bf16 v[88:91], v[174:177], v[214:217], v[88:91]
	v_mfma_f32_16x16x32_bf16 v[76:79], v[166:169], v[222:225], v[76:79]
	v_mfma_f32_16x16x32_bf16 v[72:75], v[174:177], v[222:225], v[72:75]
	v_mfma_f32_16x16x32_bf16 v[124:127], v[170:173], v[202:205], v[124:127]
	v_mfma_f32_16x16x32_bf16 v[120:123], v[178:181], v[202:205], v[120:123]
	v_mfma_f32_16x16x32_bf16 v[108:111], v[170:173], v[210:213], v[108:111]
	v_mfma_f32_16x16x32_bf16 v[104:107], v[178:181], v[210:213], v[104:107]
	v_mfma_f32_16x16x32_bf16 v[92:95], v[170:173], v[218:221], v[92:95]
	v_mfma_f32_16x16x32_bf16 v[88:91], v[178:181], v[218:221], v[88:91]
	v_mfma_f32_16x16x32_bf16 v[76:79], v[170:173], v[226:229], v[76:79]
	v_mfma_f32_16x16x32_bf16 v[72:75], v[178:181], v[226:229], v[72:75]
	v_mfma_f32_16x16x32_bf16 v[116:119], v[182:185], v[198:201], v[116:119]
	v_mfma_f32_16x16x32_bf16 v[112:115], v[190:193], v[198:201], v[112:115]
	v_mfma_f32_16x16x32_bf16 v[100:103], v[182:185], v[206:209], v[100:103]
	v_mfma_f32_16x16x32_bf16 v[96:99], v[190:193], v[206:209], v[96:99]
	v_mfma_f32_16x16x32_bf16 v[84:87], v[182:185], v[214:217], v[84:87]
	v_mfma_f32_16x16x32_bf16 v[80:83], v[190:193], v[214:217], v[80:83]
	v_mfma_f32_16x16x32_bf16 v[68:71], v[182:185], v[222:225], v[68:71]
	v_mfma_f32_16x16x32_bf16 v[64:67], v[190:193], v[222:225], v[64:67]
	v_mfma_f32_16x16x32_bf16 v[116:119], v[186:189], v[202:205], v[116:119]
	v_mfma_f32_16x16x32_bf16 v[112:115], v[194:197], v[202:205], v[112:115]
	v_mfma_f32_16x16x32_bf16 v[100:103], v[186:189], v[210:213], v[100:103]
	v_mfma_f32_16x16x32_bf16 v[96:99], v[194:197], v[210:213], v[96:99]
	v_mfma_f32_16x16x32_bf16 v[84:87], v[186:189], v[218:221], v[84:87]
	v_mfma_f32_16x16x32_bf16 v[80:83], v[194:197], v[218:221], v[80:83]
	v_mfma_f32_16x16x32_bf16 v[68:71], v[186:189], v[226:229], v[68:71]
	v_mfma_f32_16x16x32_bf16 v[64:67], v[194:197], v[226:229], v[64:67]
	s_setprio 0
	s_barrier
	s_add_i32 s48, s52, s3
	v_lshl_add_u64 v[146:147], s[70:71], 0, v[132:133]
	s_mov_b32 m0, s48
	ds_read_b128 v[198:201], v161 offset:16384
	ds_read_b128 v[202:205], v161 offset:17408
	ds_read_b128 v[206:209], v161 offset:18432
	ds_read_b128 v[210:213], v161 offset:19456
	ds_read_b128 v[214:217], v161 offset:20480
	ds_read_b128 v[218:221], v161 offset:21504
	ds_read_b128 v[222:225], v161 offset:22528
	ds_read_b128 v[226:229], v161 offset:23552
	global_load_lds_dwordx4 v[146:147], off
	s_add_i32 m0, s48, 0x2000
	s_add_u32 s50, s70, 0x40000
	v_lshl_add_u64 v[162:163], s[70:71], 0, v[136:137]
	s_addc_u32 s51, s71, 0
	s_add_i32 s48, s53, s3
	global_load_lds_dwordx4 v[162:163], off
	v_lshl_add_u64 v[230:231], s[50:51], 0, v[132:133]
	s_mov_b32 m0, s48
	v_lshl_add_u64 v[232:233], s[72:73], 0, v[134:135]
	global_load_lds_dwordx4 v[230:231], off
	v_lshl_add_u64 v[230:231], s[50:51], 0, v[136:137]
	s_add_i32 m0, s48, 0x2000
	s_nop 0
	global_load_lds_dwordx4 v[230:231], off
	v_lshl_add_u64 v[230:231], s[72:73], 0, v[130:131]
	s_mov_b32 m0, s14
	s_nop 0
	global_load_lds_dwordx4 v[230:231], off
	s_mov_b32 m0, s15
	s_nop 0
	global_load_lds_dwordx4 v[232:233], off
	s_waitcnt vmcnt(8)
	s_waitcnt lgkmcnt(0)
	s_barrier
	s_setprio 1
	s_waitcnt lgkmcnt(0)
	v_mfma_f32_16x16x32_bf16 v[60:63], v[166:169], v[198:201], v[60:63]
	v_mfma_f32_16x16x32_bf16 v[56:59], v[174:177], v[198:201], v[56:59]
	v_mfma_f32_16x16x32_bf16 v[44:47], v[166:169], v[206:209], v[44:47]
	v_mfma_f32_16x16x32_bf16 v[40:43], v[174:177], v[206:209], v[40:43]
	v_mfma_f32_16x16x32_bf16 v[28:31], v[166:169], v[214:217], v[28:31]
	v_mfma_f32_16x16x32_bf16 v[24:27], v[174:177], v[214:217], v[24:27]
	v_mfma_f32_16x16x32_bf16 v[12:15], v[166:169], v[222:225], v[12:15]
	v_mfma_f32_16x16x32_bf16 v[8:11], v[174:177], v[222:225], v[8:11]
	v_mfma_f32_16x16x32_bf16 v[60:63], v[170:173], v[202:205], v[60:63]
	v_mfma_f32_16x16x32_bf16 v[56:59], v[178:181], v[202:205], v[56:59]
	v_mfma_f32_16x16x32_bf16 v[44:47], v[170:173], v[210:213], v[44:47]
	v_mfma_f32_16x16x32_bf16 v[40:43], v[178:181], v[210:213], v[40:43]
	v_mfma_f32_16x16x32_bf16 v[28:31], v[170:173], v[218:221], v[28:31]
	v_mfma_f32_16x16x32_bf16 v[24:27], v[178:181], v[218:221], v[24:27]
	v_mfma_f32_16x16x32_bf16 v[12:15], v[170:173], v[226:229], v[12:15]
	v_mfma_f32_16x16x32_bf16 v[8:11], v[178:181], v[226:229], v[8:11]
	v_mfma_f32_16x16x32_bf16 v[52:55], v[182:185], v[198:201], v[52:55]
	v_mfma_f32_16x16x32_bf16 v[48:51], v[190:193], v[198:201], v[48:51]
	v_mfma_f32_16x16x32_bf16 v[36:39], v[182:185], v[206:209], v[36:39]
	v_mfma_f32_16x16x32_bf16 v[32:35], v[190:193], v[206:209], v[32:35]
	v_mfma_f32_16x16x32_bf16 v[20:23], v[182:185], v[214:217], v[20:23]
	v_mfma_f32_16x16x32_bf16 v[16:19], v[190:193], v[214:217], v[16:19]
	v_mfma_f32_16x16x32_bf16 v[4:7], v[182:185], v[222:225], v[4:7]
	v_mfma_f32_16x16x32_bf16 v[0:3], v[190:193], v[222:225], v[0:3]
	v_mfma_f32_16x16x32_bf16 v[52:55], v[186:189], v[202:205], v[52:55]
	v_mfma_f32_16x16x32_bf16 v[48:51], v[194:197], v[202:205], v[48:51]
	v_mfma_f32_16x16x32_bf16 v[36:39], v[186:189], v[210:213], v[36:39]
	v_mfma_f32_16x16x32_bf16 v[32:35], v[194:197], v[210:213], v[32:35]
	v_mfma_f32_16x16x32_bf16 v[20:23], v[186:189], v[218:221], v[20:23]
	v_mfma_f32_16x16x32_bf16 v[16:19], v[194:197], v[218:221], v[16:19]
	v_mfma_f32_16x16x32_bf16 v[4:7], v[186:189], v[226:229], v[4:7]
	v_mfma_f32_16x16x32_bf16 v[0:3], v[194:197], v[226:229], v[0:3]
	s_setprio 0
	s_barrier
	s_add_i32 s48, 0, 0x18000
	v_add_u32_e32 v138, s48, v141
	s_add_i32 s55, 0, 0x1c000
	ds_read_b128 v[166:169], v138
	ds_read_b128 v[170:173], v138 offset:1024
	ds_read_b128 v[174:177], v138 offset:2048
	ds_read_b128 v[178:181], v138 offset:3072
	v_add_u32_e32 v138, s55, v141
	ds_read_b128 v[182:185], v138
	ds_read_b128 v[186:189], v138 offset:1024
	ds_read_b128 v[190:193], v138 offset:2048
	ds_read_b128 v[194:197], v138 offset:3072
	s_add_u32 s50, s72, 0x40000
	s_addc_u32 s51, s73, 0
	s_mov_b32 m0, s18
	v_lshl_add_u64 v[234:235], s[50:51], 0, v[130:131]
	ds_read_b128 v[198:201], v161 offset:32768
	ds_read_b128 v[202:205], v161 offset:33792
	ds_read_b128 v[206:209], v161 offset:34816
	ds_read_b128 v[210:213], v161 offset:35840
	ds_read_b128 v[214:217], v161 offset:36864
	ds_read_b128 v[218:221], v161 offset:37888
	ds_read_b128 v[222:225], v161 offset:38912
	ds_read_b128 v[226:229], v161 offset:39936
	global_load_lds_dwordx4 v[234:235], off
	v_lshl_add_u64 v[234:235], s[50:51], 0, v[134:135]
	s_mov_b32 m0, s19
	s_nop 0
	global_load_lds_dwordx4 v[234:235], off
	s_waitcnt vmcnt(8)
	s_waitcnt lgkmcnt(0)
	s_barrier
	s_setprio 1
	s_waitcnt lgkmcnt(0)
	v_mfma_f32_16x16x32_bf16 v[124:127], v[166:169], v[198:201], v[124:127]
	v_mfma_f32_16x16x32_bf16 v[120:123], v[174:177], v[198:201], v[120:123]
	v_mfma_f32_16x16x32_bf16 v[108:111], v[166:169], v[206:209], v[108:111]
	v_mfma_f32_16x16x32_bf16 v[104:107], v[174:177], v[206:209], v[104:107]
	v_mfma_f32_16x16x32_bf16 v[92:95], v[166:169], v[214:217], v[92:95]
	v_mfma_f32_16x16x32_bf16 v[88:91], v[174:177], v[214:217], v[88:91]
	v_mfma_f32_16x16x32_bf16 v[76:79], v[166:169], v[222:225], v[76:79]
	v_mfma_f32_16x16x32_bf16 v[72:75], v[174:177], v[222:225], v[72:75]
	v_mfma_f32_16x16x32_bf16 v[124:127], v[170:173], v[202:205], v[124:127]
	v_mfma_f32_16x16x32_bf16 v[120:123], v[178:181], v[202:205], v[120:123]
	v_mfma_f32_16x16x32_bf16 v[108:111], v[170:173], v[210:213], v[108:111]
	v_mfma_f32_16x16x32_bf16 v[104:107], v[178:181], v[210:213], v[104:107]
	v_mfma_f32_16x16x32_bf16 v[92:95], v[170:173], v[218:221], v[92:95]
	v_mfma_f32_16x16x32_bf16 v[88:91], v[178:181], v[218:221], v[88:91]
	v_mfma_f32_16x16x32_bf16 v[76:79], v[170:173], v[226:229], v[76:79]
	v_mfma_f32_16x16x32_bf16 v[72:75], v[178:181], v[226:229], v[72:75]
	v_mfma_f32_16x16x32_bf16 v[116:119], v[182:185], v[198:201], v[116:119]
	v_mfma_f32_16x16x32_bf16 v[112:115], v[190:193], v[198:201], v[112:115]
	v_mfma_f32_16x16x32_bf16 v[100:103], v[182:185], v[206:209], v[100:103]
	v_mfma_f32_16x16x32_bf16 v[96:99], v[190:193], v[206:209], v[96:99]
	v_mfma_f32_16x16x32_bf16 v[84:87], v[182:185], v[214:217], v[84:87]
	v_mfma_f32_16x16x32_bf16 v[80:83], v[190:193], v[214:217], v[80:83]
	v_mfma_f32_16x16x32_bf16 v[68:71], v[182:185], v[222:225], v[68:71]
	v_mfma_f32_16x16x32_bf16 v[64:67], v[190:193], v[222:225], v[64:67]
	v_mfma_f32_16x16x32_bf16 v[116:119], v[186:189], v[202:205], v[116:119]
	v_mfma_f32_16x16x32_bf16 v[112:115], v[194:197], v[202:205], v[112:115]
	v_mfma_f32_16x16x32_bf16 v[100:103], v[186:189], v[210:213], v[100:103]
	v_mfma_f32_16x16x32_bf16 v[96:99], v[194:197], v[210:213], v[96:99]
	v_mfma_f32_16x16x32_bf16 v[84:87], v[186:189], v[218:221], v[84:87]
	v_mfma_f32_16x16x32_bf16 v[80:83], v[194:197], v[218:221], v[80:83]
	v_mfma_f32_16x16x32_bf16 v[68:71], v[186:189], v[226:229], v[68:71]
	v_mfma_f32_16x16x32_bf16 v[64:67], v[194:197], v[226:229], v[64:67]
	s_setprio 0
	s_barrier
	s_add_i32 s48, s48, s3
	v_lshl_add_u64 v[146:147], v[146:147], 0, s[26:27]
	s_mov_b32 m0, s48
	ds_read_b128 v[198:201], v161 offset:49152
	ds_read_b128 v[202:205], v161 offset:50176
	ds_read_b128 v[206:209], v161 offset:51200
	ds_read_b128 v[210:213], v161 offset:52224
	ds_read_b128 v[214:217], v161 offset:53248
	ds_read_b128 v[218:221], v161 offset:54272
	ds_read_b128 v[222:225], v161 offset:55296
	ds_read_b128 v[226:229], v161 offset:56320
	global_load_lds_dwordx4 v[146:147], off
	s_add_i32 m0, s48, 0x2000
	s_add_u32 s50, s70, 0x40080
	v_lshl_add_u64 v[146:147], v[162:163], 0, s[26:27]
	s_addc_u32 s51, s71, 0
	s_add_i32 s48, s55, s3
	global_load_lds_dwordx4 v[146:147], off
	v_lshl_add_u64 v[146:147], s[50:51], 0, v[132:133]
	s_mov_b32 m0, s48
	s_nop 0
	global_load_lds_dwordx4 v[146:147], off
	v_lshl_add_u64 v[146:147], s[50:51], 0, v[136:137]
	s_add_i32 m0, s48, 0x2000
	s_nop 0
	global_load_lds_dwordx4 v[146:147], off
	v_lshl_add_u64 v[146:147], v[230:231], 0, s[26:27]
	s_mov_b32 m0, s43
	s_nop 0
	global_load_lds_dwordx4 v[146:147], off
	v_lshl_add_u64 v[146:147], v[232:233], 0, s[26:27]
	s_mov_b32 m0, s44
	s_nop 0
	global_load_lds_dwordx4 v[146:147], off
	s_waitcnt vmcnt(8)
	s_waitcnt lgkmcnt(0)
	s_barrier
	s_setprio 1
	s_waitcnt lgkmcnt(0)
	v_mfma_f32_16x16x32_bf16 v[60:63], v[166:169], v[198:201], v[60:63]
	v_mfma_f32_16x16x32_bf16 v[56:59], v[174:177], v[198:201], v[56:59]
	v_mfma_f32_16x16x32_bf16 v[44:47], v[166:169], v[206:209], v[44:47]
	v_mfma_f32_16x16x32_bf16 v[40:43], v[174:177], v[206:209], v[40:43]
	v_mfma_f32_16x16x32_bf16 v[28:31], v[166:169], v[214:217], v[28:31]
	v_mfma_f32_16x16x32_bf16 v[24:27], v[174:177], v[214:217], v[24:27]
	v_mfma_f32_16x16x32_bf16 v[12:15], v[166:169], v[222:225], v[12:15]
	v_mfma_f32_16x16x32_bf16 v[8:11], v[174:177], v[222:225], v[8:11]
	v_mfma_f32_16x16x32_bf16 v[60:63], v[170:173], v[202:205], v[60:63]
	v_mfma_f32_16x16x32_bf16 v[56:59], v[178:181], v[202:205], v[56:59]
	v_mfma_f32_16x16x32_bf16 v[44:47], v[170:173], v[210:213], v[44:47]
	v_mfma_f32_16x16x32_bf16 v[40:43], v[178:181], v[210:213], v[40:43]
	v_mfma_f32_16x16x32_bf16 v[28:31], v[170:173], v[218:221], v[28:31]
	v_mfma_f32_16x16x32_bf16 v[24:27], v[178:181], v[218:221], v[24:27]
	v_mfma_f32_16x16x32_bf16 v[12:15], v[170:173], v[226:229], v[12:15]
	v_mfma_f32_16x16x32_bf16 v[8:11], v[178:181], v[226:229], v[8:11]
	v_mfma_f32_16x16x32_bf16 v[52:55], v[182:185], v[198:201], v[52:55]
	v_mfma_f32_16x16x32_bf16 v[48:51], v[190:193], v[198:201], v[48:51]
	v_mfma_f32_16x16x32_bf16 v[36:39], v[182:185], v[206:209], v[36:39]
	v_mfma_f32_16x16x32_bf16 v[32:35], v[190:193], v[206:209], v[32:35]
	v_mfma_f32_16x16x32_bf16 v[20:23], v[182:185], v[214:217], v[20:23]
	v_mfma_f32_16x16x32_bf16 v[16:19], v[190:193], v[214:217], v[16:19]
	v_mfma_f32_16x16x32_bf16 v[4:7], v[182:185], v[222:225], v[4:7]
	v_mfma_f32_16x16x32_bf16 v[0:3], v[190:193], v[222:225], v[0:3]
	v_mfma_f32_16x16x32_bf16 v[52:55], v[186:189], v[202:205], v[52:55]
	v_mfma_f32_16x16x32_bf16 v[48:51], v[194:197], v[202:205], v[48:51]
	v_mfma_f32_16x16x32_bf16 v[36:39], v[186:189], v[210:213], v[36:39]
	v_mfma_f32_16x16x32_bf16 v[32:35], v[194:197], v[210:213], v[32:35]
	v_mfma_f32_16x16x32_bf16 v[20:23], v[186:189], v[218:221], v[20:23]
	v_mfma_f32_16x16x32_bf16 v[16:19], v[194:197], v[218:221], v[16:19]
	v_mfma_f32_16x16x32_bf16 v[4:7], v[186:189], v[226:229], v[4:7]
	v_mfma_f32_16x16x32_bf16 v[0:3], v[194:197], v[226:229], v[0:3]
	s_setprio 0
	s_barrier
	s_add_u32 s68, s68, 0x100
	s_addc_u32 s69, s69, 0
	s_add_u32 s34, s34, 0x100
	s_addc_u32 s42, s42, 0
	s_cmp_ge_u32 s49, s2
	s_mov_b32 s48, s49
	s_cbranch_scc0 .LBB0_1506
	s_xor_b64 s[66:67], s[66:67], -1
	s_and_b64 vcc, exec, s[36:37]
	s_cbranch_vccz .LBB0_1528

.LBB0_1658:
	ds_read_b128 v[152:155], v149
	ds_read_b128 v[156:159], v149 offset:1024
	ds_read_b128 v[160:163], v149 offset:2048
	ds_read_b128 v[166:169], v149 offset:3072
	ds_read_b128 v[170:173], v150
	ds_read_b128 v[174:177], v150 offset:1024
	ds_read_b128 v[178:181], v150 offset:2048
	ds_read_b128 v[182:185], v150 offset:3072
	s_add_u32 s50, s58, 0xfffc0080
	s_addc_u32 s51, s59, -1
	s_cmp_eq_u32 s49, 12
	s_cselect_b32 s63, s33, s51
	s_cselect_b32 s62, s34, s50
	s_cselect_b32 s61, s37, s48
	s_cselect_b32 s60, s39, s42
	v_lshl_add_u64 v[218:219], s[58:59], 0, v[140:141]
	s_add_i32 m0, s18, 0xc000
	ds_read_b128 v[186:189], v151
	ds_read_b128 v[190:193], v151 offset:1024
	ds_read_b128 v[194:197], v151 offset:2048
	ds_read_b128 v[198:201], v151 offset:3072
	ds_read_b128 v[202:205], v151 offset:4096
	ds_read_b128 v[206:209], v151 offset:5120
	ds_read_b128 v[210:213], v151 offset:6144
	ds_read_b128 v[214:217], v151 offset:7168
	global_load_lds_dwordx4 v[218:219], off
	v_lshl_add_u64 v[218:219], s[58:59], 0, v[142:143]
	s_add_i32 m0, s18, 0xe000
	s_nop 0
	global_load_lds_dwordx4 v[218:219], off
	s_waitcnt vmcnt(8)
	s_waitcnt lgkmcnt(0)
	s_barrier
	s_setprio 1
	s_waitcnt lgkmcnt(0)
	v_mfma_f32_16x16x32_bf16 v[124:127], v[152:155], v[186:189], v[124:127]
	v_mfma_f32_16x16x32_bf16 v[120:123], v[160:163], v[186:189], v[120:123]
	v_mfma_f32_16x16x32_bf16 v[108:111], v[152:155], v[194:197], v[108:111]
	v_mfma_f32_16x16x32_bf16 v[104:107], v[160:163], v[194:197], v[104:107]
	v_mfma_f32_16x16x32_bf16 v[92:95], v[152:155], v[202:205], v[92:95]
	v_mfma_f32_16x16x32_bf16 v[88:91], v[160:163], v[202:205], v[88:91]
	v_mfma_f32_16x16x32_bf16 v[76:79], v[152:155], v[210:213], v[76:79]
	v_mfma_f32_16x16x32_bf16 v[72:75], v[160:163], v[210:213], v[72:75]
	v_mfma_f32_16x16x32_bf16 v[124:127], v[156:159], v[190:193], v[124:127]
	v_mfma_f32_16x16x32_bf16 v[120:123], v[166:169], v[190:193], v[120:123]
	v_mfma_f32_16x16x32_bf16 v[108:111], v[156:159], v[198:201], v[108:111]
	v_mfma_f32_16x16x32_bf16 v[104:107], v[166:169], v[198:201], v[104:107]
	v_mfma_f32_16x16x32_bf16 v[92:95], v[156:159], v[206:209], v[92:95]
	v_mfma_f32_16x16x32_bf16 v[88:91], v[166:169], v[206:209], v[88:91]
	v_mfma_f32_16x16x32_bf16 v[76:79], v[156:159], v[214:217], v[76:79]
	v_mfma_f32_16x16x32_bf16 v[72:75], v[166:169], v[214:217], v[72:75]
	v_mfma_f32_16x16x32_bf16 v[116:119], v[170:173], v[186:189], v[116:119]
	v_mfma_f32_16x16x32_bf16 v[112:115], v[178:181], v[186:189], v[112:115]
	v_mfma_f32_16x16x32_bf16 v[100:103], v[170:173], v[194:197], v[100:103]
	v_mfma_f32_16x16x32_bf16 v[96:99], v[178:181], v[194:197], v[96:99]
	v_mfma_f32_16x16x32_bf16 v[84:87], v[170:173], v[202:205], v[84:87]
	v_mfma_f32_16x16x32_bf16 v[80:83], v[178:181], v[202:205], v[80:83]
	v_mfma_f32_16x16x32_bf16 v[68:71], v[170:173], v[210:213], v[68:71]
	v_mfma_f32_16x16x32_bf16 v[64:67], v[178:181], v[210:213], v[64:67]
	v_mfma_f32_16x16x32_bf16 v[116:119], v[174:177], v[190:193], v[116:119]
	v_mfma_f32_16x16x32_bf16 v[112:115], v[182:185], v[190:193], v[112:115]
	v_mfma_f32_16x16x32_bf16 v[100:103], v[174:177], v[198:201], v[100:103]
	v_mfma_f32_16x16x32_bf16 v[96:99], v[182:185], v[198:201], v[96:99]
	v_mfma_f32_16x16x32_bf16 v[84:87], v[174:177], v[206:209], v[84:87]
	v_mfma_f32_16x16x32_bf16 v[80:83], v[182:185], v[206:209], v[80:83]
	v_mfma_f32_16x16x32_bf16 v[68:71], v[174:177], v[214:217], v[68:71]
	v_mfma_f32_16x16x32_bf16 v[64:67], v[182:185], v[214:217], v[64:67]
	s_setprio 0
	s_barrier
	s_add_i32 s50, s64, s3
	v_lshl_add_u64 v[218:219], s[60:61], 0, v[134:135]
	s_mov_b32 m0, s50
	ds_read_b128 v[186:189], v151 offset:16384
	ds_read_b128 v[190:193], v151 offset:17408
	ds_read_b128 v[194:197], v151 offset:18432
	ds_read_b128 v[198:201], v151 offset:19456
	ds_read_b128 v[202:205], v151 offset:20480
	ds_read_b128 v[206:209], v151 offset:21504
	ds_read_b128 v[210:213], v151 offset:22528
	ds_read_b128 v[214:217], v151 offset:23552
	global_load_lds_dwordx4 v[218:219], off
	s_add_i32 m0, s50, 0x2000
	s_add_u32 s50, s60, 0x40000
	v_lshl_add_u64 v[220:221], s[60:61], 0, v[130:131]
	s_addc_u32 s51, s61, 0
	s_add_i32 s57, s65, s3
	global_load_lds_dwordx4 v[220:221], off
	v_lshl_add_u64 v[222:223], s[50:51], 0, v[134:135]
	s_mov_b32 m0, s57
	v_lshl_add_u64 v[224:225], s[62:63], 0, v[132:133]
	global_load_lds_dwordx4 v[222:223], off
	v_lshl_add_u64 v[222:223], s[50:51], 0, v[130:131]
	s_add_i32 m0, s57, 0x2000
	s_nop 0
	global_load_lds_dwordx4 v[222:223], off
	v_lshl_add_u64 v[222:223], s[62:63], 0, v[136:137]
	s_mov_b32 m0, s18
	s_nop 0
	global_load_lds_dwordx4 v[222:223], off
	s_mov_b32 m0, s19
	s_nop 0
	global_load_lds_dwordx4 v[224:225], off
	s_waitcnt vmcnt(8)
	s_waitcnt lgkmcnt(0)
	s_barrier
	s_setprio 1
	s_waitcnt lgkmcnt(0)
	v_mfma_f32_16x16x32_bf16 v[60:63], v[152:155], v[186:189], v[60:63]
	v_mfma_f32_16x16x32_bf16 v[56:59], v[160:163], v[186:189], v[56:59]
	v_mfma_f32_16x16x32_bf16 v[44:47], v[152:155], v[194:197], v[44:47]
	v_mfma_f32_16x16x32_bf16 v[40:43], v[160:163], v[194:197], v[40:43]
	v_mfma_f32_16x16x32_bf16 v[28:31], v[152:155], v[202:205], v[28:31]
	v_mfma_f32_16x16x32_bf16 v[24:27], v[160:163], v[202:205], v[24:27]
	v_mfma_f32_16x16x32_bf16 v[12:15], v[152:155], v[210:213], v[12:15]
	v_mfma_f32_16x16x32_bf16 v[8:11], v[160:163], v[210:213], v[8:11]
	v_mfma_f32_16x16x32_bf16 v[60:63], v[156:159], v[190:193], v[60:63]
	v_mfma_f32_16x16x32_bf16 v[56:59], v[166:169], v[190:193], v[56:59]
	v_mfma_f32_16x16x32_bf16 v[44:47], v[156:159], v[198:201], v[44:47]
	v_mfma_f32_16x16x32_bf16 v[40:43], v[166:169], v[198:201], v[40:43]
	v_mfma_f32_16x16x32_bf16 v[28:31], v[156:159], v[206:209], v[28:31]
	v_mfma_f32_16x16x32_bf16 v[24:27], v[166:169], v[206:209], v[24:27]
	v_mfma_f32_16x16x32_bf16 v[12:15], v[156:159], v[214:217], v[12:15]
	v_mfma_f32_16x16x32_bf16 v[8:11], v[166:169], v[214:217], v[8:11]
	v_mfma_f32_16x16x32_bf16 v[52:55], v[170:173], v[186:189], v[52:55]
	v_mfma_f32_16x16x32_bf16 v[48:51], v[178:181], v[186:189], v[48:51]
	v_mfma_f32_16x16x32_bf16 v[36:39], v[170:173], v[194:197], v[36:39]
	v_mfma_f32_16x16x32_bf16 v[32:35], v[178:181], v[194:197], v[32:35]
	v_mfma_f32_16x16x32_bf16 v[20:23], v[170:173], v[202:205], v[20:23]
	v_mfma_f32_16x16x32_bf16 v[16:19], v[178:181], v[202:205], v[16:19]
	v_mfma_f32_16x16x32_bf16 v[4:7], v[170:173], v[210:213], v[4:7]
	v_mfma_f32_16x16x32_bf16 v[0:3], v[178:181], v[210:213], v[0:3]
	v_mfma_f32_16x16x32_bf16 v[52:55], v[174:177], v[190:193], v[52:55]
	v_mfma_f32_16x16x32_bf16 v[48:51], v[182:185], v[190:193], v[48:51]
	v_mfma_f32_16x16x32_bf16 v[36:39], v[174:177], v[198:201], v[36:39]
	v_mfma_f32_16x16x32_bf16 v[32:35], v[182:185], v[198:201], v[32:35]
	v_mfma_f32_16x16x32_bf16 v[20:23], v[174:177], v[206:209], v[20:23]
	v_mfma_f32_16x16x32_bf16 v[16:19], v[182:185], v[206:209], v[16:19]
	v_mfma_f32_16x16x32_bf16 v[4:7], v[174:177], v[214:217], v[4:7]
	v_mfma_f32_16x16x32_bf16 v[0:3], v[182:185], v[214:217], v[0:3]
	s_setprio 0
	s_barrier
	s_add_i32 s57, 0, 0x18000
	v_add_u32_e32 v165, s57, v148
	s_add_i32 s68, 0, 0x1c000
	ds_read_b128 v[152:155], v165
	ds_read_b128 v[156:159], v165 offset:1024
	ds_read_b128 v[160:163], v165 offset:2048
	ds_read_b128 v[166:169], v165 offset:3072
	v_add_u32_e32 v165, s68, v148
	ds_read_b128 v[170:173], v165
	ds_read_b128 v[174:177], v165 offset:1024
	ds_read_b128 v[178:181], v165 offset:2048
	ds_read_b128 v[182:185], v165 offset:3072
	s_add_u32 s50, s62, 0x40000
	s_addc_u32 s51, s63, 0
	s_mov_b32 m0, s35
	v_lshl_add_u64 v[226:227], s[50:51], 0, v[136:137]
	ds_read_b128 v[186:189], v151 offset:32768
	ds_read_b128 v[190:193], v151 offset:33792
	ds_read_b128 v[194:197], v151 offset:34816
	ds_read_b128 v[198:201], v151 offset:35840
	ds_read_b128 v[202:205], v151 offset:36864
	ds_read_b128 v[206:209], v151 offset:37888
	ds_read_b128 v[210:213], v151 offset:38912
	ds_read_b128 v[214:217], v151 offset:39936
	global_load_lds_dwordx4 v[226:227], off
	v_lshl_add_u64 v[226:227], s[50:51], 0, v[132:133]
	s_mov_b32 m0, s43
	s_nop 0
	global_load_lds_dwordx4 v[226:227], off
	s_waitcnt vmcnt(8)
	s_waitcnt lgkmcnt(0)
	s_barrier
	s_setprio 1
	s_waitcnt lgkmcnt(0)
	v_mfma_f32_16x16x32_bf16 v[124:127], v[152:155], v[186:189], v[124:127]
	v_mfma_f32_16x16x32_bf16 v[120:123], v[160:163], v[186:189], v[120:123]
	v_mfma_f32_16x16x32_bf16 v[108:111], v[152:155], v[194:197], v[108:111]
	v_mfma_f32_16x16x32_bf16 v[104:107], v[160:163], v[194:197], v[104:107]
	v_mfma_f32_16x16x32_bf16 v[92:95], v[152:155], v[202:205], v[92:95]
	v_mfma_f32_16x16x32_bf16 v[88:91], v[160:163], v[202:205], v[88:91]
	v_mfma_f32_16x16x32_bf16 v[76:79], v[152:155], v[210:213], v[76:79]
	v_mfma_f32_16x16x32_bf16 v[72:75], v[160:163], v[210:213], v[72:75]
	v_mfma_f32_16x16x32_bf16 v[124:127], v[156:159], v[190:193], v[124:127]
	v_mfma_f32_16x16x32_bf16 v[120:123], v[166:169], v[190:193], v[120:123]
	v_mfma_f32_16x16x32_bf16 v[108:111], v[156:159], v[198:201], v[108:111]
	v_mfma_f32_16x16x32_bf16 v[104:107], v[166:169], v[198:201], v[104:107]
	v_mfma_f32_16x16x32_bf16 v[92:95], v[156:159], v[206:209], v[92:95]
	v_mfma_f32_16x16x32_bf16 v[88:91], v[166:169], v[206:209], v[88:91]
	v_mfma_f32_16x16x32_bf16 v[76:79], v[156:159], v[214:217], v[76:79]
	v_mfma_f32_16x16x32_bf16 v[72:75], v[166:169], v[214:217], v[72:75]
	v_mfma_f32_16x16x32_bf16 v[116:119], v[170:173], v[186:189], v[116:119]
	v_mfma_f32_16x16x32_bf16 v[112:115], v[178:181], v[186:189], v[112:115]
	v_mfma_f32_16x16x32_bf16 v[100:103], v[170:173], v[194:197], v[100:103]
	v_mfma_f32_16x16x32_bf16 v[96:99], v[178:181], v[194:197], v[96:99]
	v_mfma_f32_16x16x32_bf16 v[84:87], v[170:173], v[202:205], v[84:87]
	v_mfma_f32_16x16x32_bf16 v[80:83], v[178:181], v[202:205], v[80:83]
	v_mfma_f32_16x16x32_bf16 v[68:71], v[170:173], v[210:213], v[68:71]
	v_mfma_f32_16x16x32_bf16 v[64:67], v[178:181], v[210:213], v[64:67]
	v_mfma_f32_16x16x32_bf16 v[116:119], v[174:177], v[190:193], v[116:119]
	v_mfma_f32_16x16x32_bf16 v[112:115], v[182:185], v[190:193], v[112:115]
	v_mfma_f32_16x16x32_bf16 v[100:103], v[174:177], v[198:201], v[100:103]
	v_mfma_f32_16x16x32_bf16 v[96:99], v[182:185], v[198:201], v[96:99]
	v_mfma_f32_16x16x32_bf16 v[84:87], v[174:177], v[206:209], v[84:87]
	v_mfma_f32_16x16x32_bf16 v[80:83], v[182:185], v[206:209], v[80:83]
	v_mfma_f32_16x16x32_bf16 v[68:71], v[174:177], v[214:217], v[68:71]
	v_mfma_f32_16x16x32_bf16 v[64:67], v[182:185], v[214:217], v[64:67]
	s_setprio 0
	s_barrier
	s_add_i32 s50, s57, s3
	v_lshl_add_u64 v[218:219], v[218:219], 0, s[24:25]
	s_mov_b32 m0, s50
	ds_read_b128 v[186:189], v151 offset:49152
	ds_read_b128 v[190:193], v151 offset:50176
	ds_read_b128 v[194:197], v151 offset:51200
	ds_read_b128 v[198:201], v151 offset:52224
	ds_read_b128 v[202:205], v151 offset:53248
	ds_read_b128 v[206:209], v151 offset:54272
	ds_read_b128 v[210:213], v151 offset:55296
	ds_read_b128 v[214:217], v151 offset:56320
	global_load_lds_dwordx4 v[218:219], off
	s_add_i32 m0, s50, 0x2000
	s_add_u32 s50, s60, 0x40080
	v_lshl_add_u64 v[218:219], v[220:221], 0, s[24:25]
	s_addc_u32 s51, s61, 0
	s_add_i32 s57, s68, s3
	global_load_lds_dwordx4 v[218:219], off
	v_lshl_add_u64 v[218:219], s[50:51], 0, v[134:135]
	s_mov_b32 m0, s57
	s_nop 0
	global_load_lds_dwordx4 v[218:219], off
	v_lshl_add_u64 v[218:219], s[50:51], 0, v[130:131]
	s_add_i32 m0, s57, 0x2000
	s_nop 0
	global_load_lds_dwordx4 v[218:219], off
	v_lshl_add_u64 v[218:219], v[222:223], 0, s[24:25]
	s_mov_b32 m0, s44
	s_nop 0
	global_load_lds_dwordx4 v[218:219], off
	v_lshl_add_u64 v[218:219], v[224:225], 0, s[24:25]
	s_mov_b32 m0, s45
	s_nop 0
	global_load_lds_dwordx4 v[218:219], off
	s_waitcnt vmcnt(8)
	s_waitcnt lgkmcnt(0)
	s_barrier
	s_setprio 1
	s_waitcnt lgkmcnt(0)
	v_mfma_f32_16x16x32_bf16 v[60:63], v[152:155], v[186:189], v[60:63]
	v_mfma_f32_16x16x32_bf16 v[56:59], v[160:163], v[186:189], v[56:59]
	v_mfma_f32_16x16x32_bf16 v[44:47], v[152:155], v[194:197], v[44:47]
	v_mfma_f32_16x16x32_bf16 v[40:43], v[160:163], v[194:197], v[40:43]
	v_mfma_f32_16x16x32_bf16 v[28:31], v[152:155], v[202:205], v[28:31]
	v_mfma_f32_16x16x32_bf16 v[24:27], v[160:163], v[202:205], v[24:27]
	v_mfma_f32_16x16x32_bf16 v[12:15], v[152:155], v[210:213], v[12:15]
	v_mfma_f32_16x16x32_bf16 v[8:11], v[160:163], v[210:213], v[8:11]
	v_mfma_f32_16x16x32_bf16 v[60:63], v[156:159], v[190:193], v[60:63]
	v_mfma_f32_16x16x32_bf16 v[56:59], v[166:169], v[190:193], v[56:59]
	v_mfma_f32_16x16x32_bf16 v[44:47], v[156:159], v[198:201], v[44:47]
	v_mfma_f32_16x16x32_bf16 v[40:43], v[166:169], v[198:201], v[40:43]
	v_mfma_f32_16x16x32_bf16 v[28:31], v[156:159], v[206:209], v[28:31]
	v_mfma_f32_16x16x32_bf16 v[24:27], v[166:169], v[206:209], v[24:27]
	v_mfma_f32_16x16x32_bf16 v[12:15], v[156:159], v[214:217], v[12:15]
	v_mfma_f32_16x16x32_bf16 v[8:11], v[166:169], v[214:217], v[8:11]
	v_mfma_f32_16x16x32_bf16 v[52:55], v[170:173], v[186:189], v[52:55]
	v_mfma_f32_16x16x32_bf16 v[48:51], v[178:181], v[186:189], v[48:51]
	v_mfma_f32_16x16x32_bf16 v[36:39], v[170:173], v[194:197], v[36:39]
	v_mfma_f32_16x16x32_bf16 v[32:35], v[178:181], v[194:197], v[32:35]
	v_mfma_f32_16x16x32_bf16 v[20:23], v[170:173], v[202:205], v[20:23]
	v_mfma_f32_16x16x32_bf16 v[16:19], v[178:181], v[202:205], v[16:19]
	v_mfma_f32_16x16x32_bf16 v[4:7], v[170:173], v[210:213], v[4:7]
	v_mfma_f32_16x16x32_bf16 v[0:3], v[178:181], v[210:213], v[0:3]
	v_mfma_f32_16x16x32_bf16 v[52:55], v[174:177], v[190:193], v[52:55]
	v_mfma_f32_16x16x32_bf16 v[48:51], v[182:185], v[190:193], v[48:51]
	v_mfma_f32_16x16x32_bf16 v[36:39], v[174:177], v[198:201], v[36:39]
	v_mfma_f32_16x16x32_bf16 v[32:35], v[182:185], v[198:201], v[32:35]
	v_mfma_f32_16x16x32_bf16 v[20:23], v[174:177], v[206:209], v[20:23]
	v_mfma_f32_16x16x32_bf16 v[16:19], v[182:185], v[206:209], v[16:19]
	v_mfma_f32_16x16x32_bf16 v[4:7], v[174:177], v[214:217], v[4:7]
	v_mfma_f32_16x16x32_bf16 v[0:3], v[182:185], v[214:217], v[0:3]
	s_setprio 0
	s_barrier
	s_add_i32 s49, s49, 2
	s_add_u32 s58, s58, 0x100
	s_addc_u32 s59, s59, 0
	s_add_u32 s42, s42, 0x100
	s_addc_u32 s48, s48, 0
	s_cmp_gt_u32 s49, 13
	s_cbranch_scc0 .LBB0_1658
	s_and_b64 vcc, exec, s[26:27]
	s_cbranch_vccz .LBB0_1661
	s_barrier

.LBB0_1735:
	ds_read_b128 v[162:165], v159
	ds_read_b128 v[166:169], v159 offset:1024
	ds_read_b128 v[170:173], v159 offset:2048
	ds_read_b128 v[174:177], v159 offset:3072
	ds_read_b128 v[178:181], v160
	ds_read_b128 v[182:185], v160 offset:1024
	ds_read_b128 v[186:189], v160 offset:2048
	ds_read_b128 v[190:193], v160 offset:3072
	s_add_i32 s68, s56, 2
	s_add_u32 s54, s52, 0x100
	s_addc_u32 s55, s53, 0
	s_cmp_eq_u32 s34, s56
	s_cselect_b32 s56, s48, s37
	s_cselect_b32 s59, s39, s55
	s_cselect_b32 s58, s38, s54
	s_cselect_b32 s57, s49, s42
	v_lshl_add_u64 v[146:147], s[52:53], 0, v[142:143]
	s_add_i32 m0, s18, 0xc000
	ds_read_b128 v[194:197], v161
	ds_read_b128 v[198:201], v161 offset:1024
	ds_read_b128 v[202:205], v161 offset:2048
	ds_read_b128 v[206:209], v161 offset:3072
	ds_read_b128 v[210:213], v161 offset:4096
	ds_read_b128 v[214:217], v161 offset:5120
	ds_read_b128 v[218:221], v161 offset:6144
	ds_read_b128 v[222:225], v161 offset:7168
	global_load_lds_dwordx4 v[146:147], off
	v_lshl_add_u64 v[146:147], s[52:53], 0, v[144:145]
	s_add_i32 m0, s18, 0xe000
	s_nop 0
	global_load_lds_dwordx4 v[146:147], off
	s_waitcnt vmcnt(8)
	s_waitcnt lgkmcnt(0)
	s_barrier
	s_setprio 1
	s_waitcnt lgkmcnt(0)
	v_mfma_f32_16x16x32_bf16 v[124:127], v[162:165], v[194:197], v[124:127]
	v_mfma_f32_16x16x32_bf16 v[120:123], v[170:173], v[194:197], v[120:123]
	v_mfma_f32_16x16x32_bf16 v[108:111], v[162:165], v[202:205], v[108:111]
	v_mfma_f32_16x16x32_bf16 v[104:107], v[170:173], v[202:205], v[104:107]
	v_mfma_f32_16x16x32_bf16 v[92:95], v[162:165], v[210:213], v[92:95]
	v_mfma_f32_16x16x32_bf16 v[88:91], v[170:173], v[210:213], v[88:91]
	v_mfma_f32_16x16x32_bf16 v[76:79], v[162:165], v[218:221], v[76:79]
	v_mfma_f32_16x16x32_bf16 v[72:75], v[170:173], v[218:221], v[72:75]
	v_mfma_f32_16x16x32_bf16 v[124:127], v[166:169], v[198:201], v[124:127]
	v_mfma_f32_16x16x32_bf16 v[120:123], v[174:177], v[198:201], v[120:123]
	v_mfma_f32_16x16x32_bf16 v[108:111], v[166:169], v[206:209], v[108:111]
	v_mfma_f32_16x16x32_bf16 v[104:107], v[174:177], v[206:209], v[104:107]
	v_mfma_f32_16x16x32_bf16 v[92:95], v[166:169], v[214:217], v[92:95]
	v_mfma_f32_16x16x32_bf16 v[88:91], v[174:177], v[214:217], v[88:91]
	v_mfma_f32_16x16x32_bf16 v[76:79], v[166:169], v[222:225], v[76:79]
	v_mfma_f32_16x16x32_bf16 v[72:75], v[174:177], v[222:225], v[72:75]
	v_mfma_f32_16x16x32_bf16 v[116:119], v[178:181], v[194:197], v[116:119]
	v_mfma_f32_16x16x32_bf16 v[112:115], v[186:189], v[194:197], v[112:115]
	v_mfma_f32_16x16x32_bf16 v[100:103], v[178:181], v[202:205], v[100:103]
	v_mfma_f32_16x16x32_bf16 v[96:99], v[186:189], v[202:205], v[96:99]
	v_mfma_f32_16x16x32_bf16 v[84:87], v[178:181], v[210:213], v[84:87]
	v_mfma_f32_16x16x32_bf16 v[80:83], v[186:189], v[210:213], v[80:83]
	v_mfma_f32_16x16x32_bf16 v[68:71], v[178:181], v[218:221], v[68:71]
	v_mfma_f32_16x16x32_bf16 v[64:67], v[186:189], v[218:221], v[64:67]
	v_mfma_f32_16x16x32_bf16 v[116:119], v[182:185], v[198:201], v[116:119]
	v_mfma_f32_16x16x32_bf16 v[112:115], v[190:193], v[198:201], v[112:115]
	v_mfma_f32_16x16x32_bf16 v[100:103], v[182:185], v[206:209], v[100:103]
	v_mfma_f32_16x16x32_bf16 v[96:99], v[190:193], v[206:209], v[96:99]
	v_mfma_f32_16x16x32_bf16 v[84:87], v[182:185], v[214:217], v[84:87]
	v_mfma_f32_16x16x32_bf16 v[80:83], v[190:193], v[214:217], v[80:83]
	v_mfma_f32_16x16x32_bf16 v[68:71], v[182:185], v[222:225], v[68:71]
	v_mfma_f32_16x16x32_bf16 v[64:67], v[190:193], v[222:225], v[64:67]
	s_setprio 0
	s_barrier
	s_add_i32 s52, s63, s15
	v_lshl_add_u64 v[146:147], s[56:57], 0, v[132:133]
	s_mov_b32 m0, s52
	ds_read_b128 v[194:197], v161 offset:16384
	ds_read_b128 v[198:201], v161 offset:17408
	ds_read_b128 v[202:205], v161 offset:18432
	ds_read_b128 v[206:209], v161 offset:19456
	ds_read_b128 v[210:213], v161 offset:20480
	ds_read_b128 v[214:217], v161 offset:21504
	ds_read_b128 v[218:221], v161 offset:22528
	ds_read_b128 v[222:225], v161 offset:23552
	global_load_lds_dwordx4 v[146:147], off
	s_add_i32 m0, s52, 0x2000
	s_add_u32 s52, s56, 0xb0000
	v_lshl_add_u64 v[226:227], s[56:57], 0, v[136:137]
	s_addc_u32 s53, s57, 0
	s_add_i32 s69, s64, s15
	global_load_lds_dwordx4 v[226:227], off
	v_lshl_add_u64 v[228:229], s[52:53], 0, v[132:133]
	s_mov_b32 m0, s69
	v_lshl_add_u64 v[230:231], s[58:59], 0, v[134:135]
	global_load_lds_dwordx4 v[228:229], off
	v_lshl_add_u64 v[228:229], s[52:53], 0, v[136:137]
	s_add_i32 m0, s69, 0x2000
	s_nop 0
	global_load_lds_dwordx4 v[228:229], off
	v_lshl_add_u64 v[228:229], s[58:59], 0, v[130:131]
	s_mov_b32 m0, s18
	s_nop 0
	global_load_lds_dwordx4 v[228:229], off
	s_mov_b32 m0, s19
	s_nop 0
	global_load_lds_dwordx4 v[230:231], off
	s_waitcnt vmcnt(8)
	s_waitcnt lgkmcnt(0)
	s_barrier
	s_setprio 1
	s_waitcnt lgkmcnt(0)
	v_mfma_f32_16x16x32_bf16 v[60:63], v[162:165], v[194:197], v[60:63]
	v_mfma_f32_16x16x32_bf16 v[56:59], v[170:173], v[194:197], v[56:59]
	v_mfma_f32_16x16x32_bf16 v[44:47], v[162:165], v[202:205], v[44:47]
	v_mfma_f32_16x16x32_bf16 v[40:43], v[170:173], v[202:205], v[40:43]
	v_mfma_f32_16x16x32_bf16 v[28:31], v[162:165], v[210:213], v[28:31]
	v_mfma_f32_16x16x32_bf16 v[24:27], v[170:173], v[210:213], v[24:27]
	v_mfma_f32_16x16x32_bf16 v[12:15], v[162:165], v[218:221], v[12:15]
	v_mfma_f32_16x16x32_bf16 v[8:11], v[170:173], v[218:221], v[8:11]
	v_mfma_f32_16x16x32_bf16 v[60:63], v[166:169], v[198:201], v[60:63]
	v_mfma_f32_16x16x32_bf16 v[56:59], v[174:177], v[198:201], v[56:59]
	v_mfma_f32_16x16x32_bf16 v[44:47], v[166:169], v[206:209], v[44:47]
	v_mfma_f32_16x16x32_bf16 v[40:43], v[174:177], v[206:209], v[40:43]
	v_mfma_f32_16x16x32_bf16 v[28:31], v[166:169], v[214:217], v[28:31]
	v_mfma_f32_16x16x32_bf16 v[24:27], v[174:177], v[214:217], v[24:27]
	v_mfma_f32_16x16x32_bf16 v[12:15], v[166:169], v[222:225], v[12:15]
	v_mfma_f32_16x16x32_bf16 v[8:11], v[174:177], v[222:225], v[8:11]
	v_mfma_f32_16x16x32_bf16 v[52:55], v[178:181], v[194:197], v[52:55]
	v_mfma_f32_16x16x32_bf16 v[48:51], v[186:189], v[194:197], v[48:51]
	v_mfma_f32_16x16x32_bf16 v[36:39], v[178:181], v[202:205], v[36:39]
	v_mfma_f32_16x16x32_bf16 v[32:35], v[186:189], v[202:205], v[32:35]
	v_mfma_f32_16x16x32_bf16 v[20:23], v[178:181], v[210:213], v[20:23]
	v_mfma_f32_16x16x32_bf16 v[16:19], v[186:189], v[210:213], v[16:19]
	v_mfma_f32_16x16x32_bf16 v[4:7], v[178:181], v[218:221], v[4:7]
	v_mfma_f32_16x16x32_bf16 v[0:3], v[186:189], v[218:221], v[0:3]
	v_mfma_f32_16x16x32_bf16 v[52:55], v[182:185], v[198:201], v[52:55]
	v_mfma_f32_16x16x32_bf16 v[48:51], v[190:193], v[198:201], v[48:51]
	v_mfma_f32_16x16x32_bf16 v[36:39], v[182:185], v[206:209], v[36:39]
	v_mfma_f32_16x16x32_bf16 v[32:35], v[190:193], v[206:209], v[32:35]
	v_mfma_f32_16x16x32_bf16 v[20:23], v[182:185], v[214:217], v[20:23]
	v_mfma_f32_16x16x32_bf16 v[16:19], v[190:193], v[214:217], v[16:19]
	v_mfma_f32_16x16x32_bf16 v[4:7], v[182:185], v[222:225], v[4:7]
	v_mfma_f32_16x16x32_bf16 v[0:3], v[190:193], v[222:225], v[0:3]
	s_setprio 0
	s_barrier
	s_add_i32 s69, 0, 0x18000
	v_add_u32_e32 v138, s69, v141
	s_add_i32 s70, 0, 0x1c000
	ds_read_b128 v[162:165], v138
	ds_read_b128 v[166:169], v138 offset:1024
	ds_read_b128 v[170:173], v138 offset:2048
	ds_read_b128 v[174:177], v138 offset:3072
	v_add_u32_e32 v138, s70, v141
	ds_read_b128 v[178:181], v138
	ds_read_b128 v[182:185], v138 offset:1024
	ds_read_b128 v[186:189], v138 offset:2048
	ds_read_b128 v[190:193], v138 offset:3072
	s_add_u32 s52, s58, 0xb0000
	s_addc_u32 s53, s59, 0
	s_mov_b32 m0, s35
	v_lshl_add_u64 v[232:233], s[52:53], 0, v[130:131]
	ds_read_b128 v[194:197], v161 offset:32768
	ds_read_b128 v[198:201], v161 offset:33792
	ds_read_b128 v[202:205], v161 offset:34816
	ds_read_b128 v[206:209], v161 offset:35840
	ds_read_b128 v[210:213], v161 offset:36864
	ds_read_b128 v[214:217], v161 offset:37888
	ds_read_b128 v[218:221], v161 offset:38912
	ds_read_b128 v[222:225], v161 offset:39936
	global_load_lds_dwordx4 v[232:233], off
	v_lshl_add_u64 v[232:233], s[52:53], 0, v[134:135]
	s_mov_b32 m0, s43
	s_nop 0
	global_load_lds_dwordx4 v[232:233], off
	s_waitcnt vmcnt(8)
	s_waitcnt lgkmcnt(0)
	s_barrier
	s_setprio 1
	s_waitcnt lgkmcnt(0)
	v_mfma_f32_16x16x32_bf16 v[124:127], v[162:165], v[194:197], v[124:127]
	v_mfma_f32_16x16x32_bf16 v[120:123], v[170:173], v[194:197], v[120:123]
	v_mfma_f32_16x16x32_bf16 v[108:111], v[162:165], v[202:205], v[108:111]
	v_mfma_f32_16x16x32_bf16 v[104:107], v[170:173], v[202:205], v[104:107]
	v_mfma_f32_16x16x32_bf16 v[92:95], v[162:165], v[210:213], v[92:95]
	v_mfma_f32_16x16x32_bf16 v[88:91], v[170:173], v[210:213], v[88:91]
	v_mfma_f32_16x16x32_bf16 v[76:79], v[162:165], v[218:221], v[76:79]
	v_mfma_f32_16x16x32_bf16 v[72:75], v[170:173], v[218:221], v[72:75]
	v_mfma_f32_16x16x32_bf16 v[124:127], v[166:169], v[198:201], v[124:127]
	v_mfma_f32_16x16x32_bf16 v[120:123], v[174:177], v[198:201], v[120:123]
	v_mfma_f32_16x16x32_bf16 v[108:111], v[166:169], v[206:209], v[108:111]
	v_mfma_f32_16x16x32_bf16 v[104:107], v[174:177], v[206:209], v[104:107]
	v_mfma_f32_16x16x32_bf16 v[92:95], v[166:169], v[214:217], v[92:95]
	v_mfma_f32_16x16x32_bf16 v[88:91], v[174:177], v[214:217], v[88:91]
	v_mfma_f32_16x16x32_bf16 v[76:79], v[166:169], v[222:225], v[76:79]
	v_mfma_f32_16x16x32_bf16 v[72:75], v[174:177], v[222:225], v[72:75]
	v_mfma_f32_16x16x32_bf16 v[116:119], v[178:181], v[194:197], v[116:119]
	v_mfma_f32_16x16x32_bf16 v[112:115], v[186:189], v[194:197], v[112:115]
	v_mfma_f32_16x16x32_bf16 v[100:103], v[178:181], v[202:205], v[100:103]
	v_mfma_f32_16x16x32_bf16 v[96:99], v[186:189], v[202:205], v[96:99]
	v_mfma_f32_16x16x32_bf16 v[84:87], v[178:181], v[210:213], v[84:87]
	v_mfma_f32_16x16x32_bf16 v[80:83], v[186:189], v[210:213], v[80:83]
	v_mfma_f32_16x16x32_bf16 v[68:71], v[178:181], v[218:221], v[68:71]
	v_mfma_f32_16x16x32_bf16 v[64:67], v[186:189], v[218:221], v[64:67]
	v_mfma_f32_16x16x32_bf16 v[116:119], v[182:185], v[198:201], v[116:119]
	v_mfma_f32_16x16x32_bf16 v[112:115], v[190:193], v[198:201], v[112:115]
	v_mfma_f32_16x16x32_bf16 v[100:103], v[182:185], v[206:209], v[100:103]
	v_mfma_f32_16x16x32_bf16 v[96:99], v[190:193], v[206:209], v[96:99]
	v_mfma_f32_16x16x32_bf16 v[84:87], v[182:185], v[214:217], v[84:87]
	v_mfma_f32_16x16x32_bf16 v[80:83], v[190:193], v[214:217], v[80:83]
	v_mfma_f32_16x16x32_bf16 v[68:71], v[182:185], v[222:225], v[68:71]
	v_mfma_f32_16x16x32_bf16 v[64:67], v[190:193], v[222:225], v[64:67]
	s_setprio 0
	s_barrier
	s_add_i32 s52, s69, s15
	v_lshl_add_u64 v[146:147], v[146:147], 0, s[22:23]
	s_mov_b32 m0, s52
	ds_read_b128 v[194:197], v161 offset:49152
	ds_read_b128 v[198:201], v161 offset:50176
	ds_read_b128 v[202:205], v161 offset:51200
	ds_read_b128 v[206:209], v161 offset:52224
	ds_read_b128 v[210:213], v161 offset:53248
	ds_read_b128 v[214:217], v161 offset:54272
	ds_read_b128 v[218:221], v161 offset:55296
	ds_read_b128 v[222:225], v161 offset:56320
	global_load_lds_dwordx4 v[146:147], off
	s_add_i32 m0, s52, 0x2000
	s_add_u32 s52, s56, 0xb0080
	v_lshl_add_u64 v[146:147], v[226:227], 0, s[22:23]
	s_addc_u32 s53, s57, 0
	s_add_i32 s56, s70, s15
	global_load_lds_dwordx4 v[146:147], off
	v_lshl_add_u64 v[146:147], s[52:53], 0, v[132:133]
	s_mov_b32 m0, s56
	s_nop 0
	global_load_lds_dwordx4 v[146:147], off
	v_lshl_add_u64 v[146:147], s[52:53], 0, v[136:137]
	s_add_i32 m0, s56, 0x2000
	s_nop 0
	global_load_lds_dwordx4 v[146:147], off
	v_lshl_add_u64 v[146:147], v[228:229], 0, s[22:23]
	s_mov_b32 m0, s46
	s_nop 0
	global_load_lds_dwordx4 v[146:147], off
	v_lshl_add_u64 v[146:147], v[230:231], 0, s[22:23]
	s_mov_b32 m0, s47
	s_nop 0
	global_load_lds_dwordx4 v[146:147], off
	s_waitcnt vmcnt(8)
	s_waitcnt lgkmcnt(0)
	s_barrier
	s_setprio 1
	s_waitcnt lgkmcnt(0)
	v_mfma_f32_16x16x32_bf16 v[60:63], v[162:165], v[194:197], v[60:63]
	v_mfma_f32_16x16x32_bf16 v[56:59], v[170:173], v[194:197], v[56:59]
	v_mfma_f32_16x16x32_bf16 v[44:47], v[162:165], v[202:205], v[44:47]
	v_mfma_f32_16x16x32_bf16 v[40:43], v[170:173], v[202:205], v[40:43]
	v_mfma_f32_16x16x32_bf16 v[28:31], v[162:165], v[210:213], v[28:31]
	v_mfma_f32_16x16x32_bf16 v[24:27], v[170:173], v[210:213], v[24:27]
	v_mfma_f32_16x16x32_bf16 v[12:15], v[162:165], v[218:221], v[12:15]
	v_mfma_f32_16x16x32_bf16 v[8:11], v[170:173], v[218:221], v[8:11]
	v_mfma_f32_16x16x32_bf16 v[60:63], v[166:169], v[198:201], v[60:63]
	v_mfma_f32_16x16x32_bf16 v[56:59], v[174:177], v[198:201], v[56:59]
	v_mfma_f32_16x16x32_bf16 v[44:47], v[166:169], v[206:209], v[44:47]
	v_mfma_f32_16x16x32_bf16 v[40:43], v[174:177], v[206:209], v[40:43]
	v_mfma_f32_16x16x32_bf16 v[28:31], v[166:169], v[214:217], v[28:31]
	v_mfma_f32_16x16x32_bf16 v[24:27], v[174:177], v[214:217], v[24:27]
	v_mfma_f32_16x16x32_bf16 v[12:15], v[166:169], v[222:225], v[12:15]
	v_mfma_f32_16x16x32_bf16 v[8:11], v[174:177], v[222:225], v[8:11]
	v_mfma_f32_16x16x32_bf16 v[52:55], v[178:181], v[194:197], v[52:55]
	v_mfma_f32_16x16x32_bf16 v[48:51], v[186:189], v[194:197], v[48:51]
	v_mfma_f32_16x16x32_bf16 v[36:39], v[178:181], v[202:205], v[36:39]
	v_mfma_f32_16x16x32_bf16 v[32:35], v[186:189], v[202:205], v[32:35]
	v_mfma_f32_16x16x32_bf16 v[20:23], v[178:181], v[210:213], v[20:23]
	v_mfma_f32_16x16x32_bf16 v[16:19], v[186:189], v[210:213], v[16:19]
	v_mfma_f32_16x16x32_bf16 v[4:7], v[178:181], v[218:221], v[4:7]
	v_mfma_f32_16x16x32_bf16 v[0:3], v[186:189], v[218:221], v[0:3]
	v_mfma_f32_16x16x32_bf16 v[52:55], v[182:185], v[198:201], v[52:55]
	v_mfma_f32_16x16x32_bf16 v[48:51], v[190:193], v[198:201], v[48:51]
	v_mfma_f32_16x16x32_bf16 v[36:39], v[182:185], v[206:209], v[36:39]
	v_mfma_f32_16x16x32_bf16 v[32:35], v[190:193], v[206:209], v[32:35]
	v_mfma_f32_16x16x32_bf16 v[20:23], v[182:185], v[214:217], v[20:23]
	v_mfma_f32_16x16x32_bf16 v[16:19], v[190:193], v[214:217], v[16:19]
	v_mfma_f32_16x16x32_bf16 v[4:7], v[182:185], v[222:225], v[4:7]
	v_mfma_f32_16x16x32_bf16 v[0:3], v[190:193], v[222:225], v[0:3]
	s_setprio 0
	s_barrier
	s_add_u32 s37, s37, 0x100
	s_addc_u32 s42, s42, 0
	s_cmp_ge_u32 s68, s33
	s_mov_b64 s[52:53], s[54:55]
	s_mov_b32 s56, s68
	s_cbranch_scc0 .LBB0_1735
	s_xor_b64 s[50:51], s[50:51], -1
	s_and_b64 vcc, exec, s[24:25]
	s_cbranch_vccz .LBB0_1757
